# row-scale LDS reads of the A/gate/FFN1 epilogues hoisted to one batch at epilogue start
# baseline (speedup 1.0000x reference)
; #define LAS __attribute__((address_space(3)))
; __device__ __forceinline__ float sigmoidf_(float x) { return __builtin_amdgcn_rcpf(1.f + __expf(-x)); }
;     __device__ __forceinline__ void operator()(const f32x4 (&acc)[2][2][4][2], const Unit& u, int wr, int wc, int fr, int fq, const LAS float* rsl) const {
;         const int row0 = u.pm * 256 + wr * 64 + fr;
; #pragma unroll
;         for (int ai = 0; ai < 2; ++ai)
; #pragma unroll
;             for (int m = 0; m < 4; ++m) {
;                 const int row = row0 + ai * 128 + m * 16; const float rs = rsl[ai * 128 + wr * 64 + m * 16 + fr];
;                 f32x4 o[2];
; #pragma unroll
;                 for (int n = 0; n < 2; ++n)
; #pragma unroll
;                     for (int j = 0; j < 4; ++j) { const float gt = acc[ai][0][m][n][j] * rs, up = acc[ai][1][m][n][j] * rs; o[n][j] = gt * sigmoidf_(gt) * up; }
;                 *(u32x4*)(ACT + (size_t)row * DFF + u.pn * 128 + wc * 32 + 8 * fq) = pack8(o[0], o[1]);
;                 asm volatile("" ::: "memory");
;             }
.LBB0_209:
	v_add_u32_e32 v159, s51, v156
	ds_read_b32 v168, v159
	ds_read_b32 v169, v159 offset:64
	ds_read_b32 v170, v159 offset:128
	ds_read_b32 v171, v159 offset:192
	ds_read_b32 v172, v159 offset:512
	ds_read_b32 v173, v159 offset:576
	ds_read_b32 v174, v159 offset:640
	ds_read_b32 v175, v159 offset:704
	s_waitcnt lgkmcnt(0)
	s_nop 1
	v_mov_b32_e32 v160, v168
	s_lshl_b32 s12, s50, 7
	v_lshl_add_u32 v158, s24, 8, v142
	s_ashr_i32 s13, s12, 31
	s_movk_i32 s17, 0x1600
	s_waitcnt lgkmcnt(0)
	v_pk_mul_f32 v[124:125], v[124:125], v[160:161] op_sel_hi:[1,0]
	v_pk_mul_f32 v[120:121], v[120:121], v[160:161] op_sel_hi:[1,0]
	v_mul_f32_e32 v152, 0xbfb8aa3b, v124
	v_exp_f32_e32 v152, v152
	v_pk_mul_f32 v[122:123], v[122:123], v[160:161] op_sel_hi:[1,0]
	v_pk_mul_f32 v[116:117], v[116:117], v[160:161] op_sel_hi:[1,0]
	v_pk_mul_f32 v[112:113], v[112:113], v[160:161] op_sel_hi:[1,0]
	v_add_f32_e32 v152, 1.0, v152
	v_rcp_f32_e32 v162, v152
	v_mul_f32_e32 v152, 0xbfb8aa3b, v125
	v_exp_f32_e32 v152, v152
	v_pk_mul_f32 v[114:115], v[114:115], v[160:161] op_sel_hi:[1,0]
	s_lshl_b64 s[12:13], s[12:13], 1
	s_and_b64 vcc, exec, s[10:11]
	v_add_f32_e32 v152, 1.0, v152
	v_rcp_f32_e32 v163, v152
	s_nop 0
	v_pk_mul_f32 v[124:125], v[124:125], v[162:163]
	s_nop 0
	v_pk_mul_f32 v[120:121], v[120:121], v[124:125]
	v_pk_mul_f32 v[124:125], v[126:127], v[160:161] op_sel_hi:[1,0]
	s_nop 0
	v_mul_f32_e32 v126, 0xbfb8aa3b, v124
	v_mul_f32_e32 v127, 0xbfb8aa3b, v125
	v_exp_f32_e32 v126, v126
	v_exp_f32_e32 v127, v127
	v_add_f32_e32 v126, 1.0, v126
	v_add_f32_e32 v127, 1.0, v127
	v_rcp_f32_e32 v126, v126
	v_rcp_f32_e32 v127, v127
	s_nop 0
	v_pk_mul_f32 v[124:125], v[124:125], v[126:127]
	s_nop 0
	v_pk_mul_f32 v[122:123], v[122:123], v[124:125]
	v_mul_f32_e32 v124, 0xbfb8aa3b, v116
	v_mul_f32_e32 v125, 0xbfb8aa3b, v117
	v_exp_f32_e32 v124, v124
	v_exp_f32_e32 v125, v125
	v_add_f32_e32 v124, 1.0, v124
	v_add_f32_e32 v125, 1.0, v125
	v_rcp_f32_e32 v124, v124
	v_rcp_f32_e32 v125, v125
	s_nop 0
	v_pk_mul_f32 v[116:117], v[116:117], v[124:125]
	s_nop 0
	v_pk_mul_f32 v[112:113], v[112:113], v[116:117]
	v_pk_mul_f32 v[116:117], v[118:119], v[160:161] op_sel_hi:[1,0]
	s_nop 0
	v_mul_f32_e32 v118, 0xbfb8aa3b, v116
	v_mul_f32_e32 v119, 0xbfb8aa3b, v117
	v_exp_f32_e32 v118, v118
	v_exp_f32_e32 v119, v119
	v_add_f32_e32 v118, 1.0, v118
	v_add_f32_e32 v119, 1.0, v119
	v_rcp_f32_e32 v118, v118
	v_rcp_f32_e32 v119, v119
	s_nop 0
	v_pk_mul_f32 v[116:117], v[116:117], v[118:119]
	s_nop 0
	v_pk_mul_f32 v[118:119], v[114:115], v[116:117]
	v_cvt_pk_bf16_f32 v116, v112, v113
	v_mov_b64_e32 v[112:113], s[72:73]
	v_cvt_pk_bf16_f32 v117, v118, v119
	v_mad_i64_i32 v[118:119], s[26:27], v158, s17, v[112:113]
	v_lshl_add_u64 v[118:119], v[118:119], 0, s[12:13]
	v_lshl_add_u64 v[118:119], v[118:119], 0, s[68:69]
	v_cvt_pk_bf16_f32 v114, v120, v121
	v_cvt_pk_bf16_f32 v115, v122, v123
	v_lshl_add_u64 v[118:119], v[118:119], 0, v[146:147]
	global_store_dwordx4 v[118:119], v[114:117], off
	s_nop 1
	v_mov_b32_e32 v114, v169
	s_waitcnt lgkmcnt(0)
	v_pk_mul_f32 v[108:109], v[108:109], v[114:115] op_sel_hi:[1,0]
	s_nop 0
	v_mul_f32_e32 v115, 0xbfb8aa3b, v108
	v_exp_f32_e32 v115, v115
	s_nop 0
	v_add_f32_e32 v115, 1.0, v115
	v_rcp_f32_e32 v116, v115
	v_pk_mul_f32 v[104:105], v[104:105], v[114:115] op_sel_hi:[1,0]
	v_mul_f32_e32 v115, 0xbfb8aa3b, v109
	v_exp_f32_e32 v115, v115
	s_nop 0
	v_add_f32_e32 v115, 1.0, v115
	v_rcp_f32_e32 v117, v115
	v_pk_mul_f32 v[106:107], v[106:107], v[114:115] op_sel_hi:[1,0]
	v_pk_mul_f32 v[100:101], v[100:101], v[114:115] op_sel_hi:[1,0]
	v_pk_mul_f32 v[96:97], v[96:97], v[114:115] op_sel_hi:[1,0]
	v_pk_mul_f32 v[108:109], v[108:109], v[116:117]
	v_pk_mul_f32 v[98:99], v[98:99], v[114:115] op_sel_hi:[1,0]
	v_pk_mul_f32 v[104:105], v[104:105], v[108:109]
	v_pk_mul_f32 v[108:109], v[110:111], v[114:115] op_sel_hi:[1,0]
	s_nop 0
	v_mul_f32_e32 v110, 0xbfb8aa3b, v108
	v_mul_f32_e32 v111, 0xbfb8aa3b, v109
	v_exp_f32_e32 v110, v110
	v_exp_f32_e32 v111, v111
	v_add_f32_e32 v110, 1.0, v110
	v_add_f32_e32 v111, 1.0, v111
	v_rcp_f32_e32 v110, v110
	v_rcp_f32_e32 v111, v111
	s_nop 0
	v_pk_mul_f32 v[108:109], v[108:109], v[110:111]
	s_nop 0
	v_pk_mul_f32 v[106:107], v[106:107], v[108:109]
	v_mul_f32_e32 v108, 0xbfb8aa3b, v100
	v_mul_f32_e32 v109, 0xbfb8aa3b, v101
	v_exp_f32_e32 v108, v108
	v_exp_f32_e32 v109, v109
	v_add_f32_e32 v108, 1.0, v108
	v_add_f32_e32 v109, 1.0, v109
	v_rcp_f32_e32 v108, v108
	v_rcp_f32_e32 v109, v109
	s_nop 0
	v_pk_mul_f32 v[100:101], v[100:101], v[108:109]
	s_nop 0
	v_pk_mul_f32 v[100:101], v[96:97], v[100:101]
	v_pk_mul_f32 v[96:97], v[102:103], v[114:115] op_sel_hi:[1,0]
	v_or_b32_e32 v108, 16, v158
	v_mul_f32_e32 v102, 0xbfb8aa3b, v96
	v_mul_f32_e32 v103, 0xbfb8aa3b, v97
	v_exp_f32_e32 v102, v102
	v_exp_f32_e32 v103, v103
	v_add_f32_e32 v102, 1.0, v102
	v_add_f32_e32 v103, 1.0, v103
	v_rcp_f32_e32 v102, v102
	v_rcp_f32_e32 v103, v103
	s_nop 0
	v_pk_mul_f32 v[96:97], v[96:97], v[102:103]
	s_nop 0
	v_pk_mul_f32 v[102:103], v[98:99], v[96:97]
	v_cvt_pk_bf16_f32 v98, v100, v101
	v_mad_i64_i32 v[100:101], s[26:27], v108, s17, v[112:113]
	v_lshl_add_u64 v[100:101], v[100:101], 0, s[12:13]
	v_lshl_add_u64 v[100:101], v[100:101], 0, s[68:69]
	v_cvt_pk_bf16_f32 v96, v104, v105
	v_cvt_pk_bf16_f32 v97, v106, v107
	v_cvt_pk_bf16_f32 v99, v102, v103
	v_lshl_add_u64 v[100:101], v[100:101], 0, v[146:147]
	global_store_dwordx4 v[100:101], v[96:99], off
	s_nop 1
	v_mov_b32_e32 v96, v170
	s_waitcnt lgkmcnt(0)
; #define LAS __attribute__((address_space(3)))
; __device__ __forceinline__ float sigmoidf_(float x) { return __builtin_amdgcn_rcpf(1.f + __expf(-x)); }
;     __device__ __forceinline__ void operator()(const f32x4 (&acc)[2][2][4][2], const Unit& u, int wr, int wc, int fr, int fq, const LAS float* rsl) const {
;         const int row0 = u.pm * 256 + wr * 64 + fr;
; #pragma unroll
;         for (int ai = 0; ai < 2; ++ai)
; #pragma unroll
;             for (int m = 0; m < 4; ++m) {
;                 const int row = row0 + ai * 128 + m * 16; const float rs = rsl[ai * 128 + wr * 64 + m * 16 + fr];
;                 f32x4 o[2];
; #pragma unroll
;                 for (int n = 0; n < 2; ++n)
; #pragma unroll
;                     for (int j = 0; j < 4; ++j) { const float gt = acc[ai][0][m][n][j] * rs, up = acc[ai][1][m][n][j] * rs; o[n][j] = gt * sigmoidf_(gt) * up; }
;                 *(u32x4*)(ACT + (size_t)row * DFF + u.pn * 128 + wc * 32 + 8 * fq) = pack8(o[0], o[1]);
;                 asm volatile("" ::: "memory");
;             }
	v_pk_mul_f32 v[92:93], v[92:93], v[96:97] op_sel_hi:[1,0]
	s_nop 0
	v_mul_f32_e32 v97, 0xbfb8aa3b, v92
	v_exp_f32_e32 v97, v97
	s_nop 0
	v_add_f32_e32 v97, 1.0, v97
	v_rcp_f32_e32 v98, v97
	v_pk_mul_f32 v[88:89], v[88:89], v[96:97] op_sel_hi:[1,0]
	v_mul_f32_e32 v97, 0xbfb8aa3b, v93
	v_exp_f32_e32 v97, v97
	s_nop 0
	v_add_f32_e32 v97, 1.0, v97
	v_rcp_f32_e32 v99, v97
	v_pk_mul_f32 v[90:91], v[90:91], v[96:97] op_sel_hi:[1,0]
	v_pk_mul_f32 v[84:85], v[84:85], v[96:97] op_sel_hi:[1,0]
	v_pk_mul_f32 v[80:81], v[80:81], v[96:97] op_sel_hi:[1,0]
	v_pk_mul_f32 v[92:93], v[92:93], v[98:99]
	v_pk_mul_f32 v[82:83], v[82:83], v[96:97] op_sel_hi:[1,0]
	v_pk_mul_f32 v[88:89], v[88:89], v[92:93]
	v_pk_mul_f32 v[92:93], v[94:95], v[96:97] op_sel_hi:[1,0]
	s_nop 0
	v_mul_f32_e32 v94, 0xbfb8aa3b, v92
	v_mul_f32_e32 v95, 0xbfb8aa3b, v93
	v_exp_f32_e32 v94, v94
	v_exp_f32_e32 v95, v95
	v_add_f32_e32 v94, 1.0, v94
	v_add_f32_e32 v95, 1.0, v95
	v_rcp_f32_e32 v94, v94
	v_rcp_f32_e32 v95, v95
	s_nop 0
	v_pk_mul_f32 v[92:93], v[92:93], v[94:95]
	s_nop 0
	v_pk_mul_f32 v[90:91], v[90:91], v[92:93]
	v_mul_f32_e32 v92, 0xbfb8aa3b, v84
	v_mul_f32_e32 v93, 0xbfb8aa3b, v85
	v_exp_f32_e32 v92, v92
	v_exp_f32_e32 v93, v93
	v_add_f32_e32 v92, 1.0, v92
	v_add_f32_e32 v93, 1.0, v93
	v_rcp_f32_e32 v92, v92
	v_rcp_f32_e32 v93, v93
	s_nop 0
	v_pk_mul_f32 v[84:85], v[84:85], v[92:93]
	s_nop 0
	v_pk_mul_f32 v[84:85], v[80:81], v[84:85]
	v_pk_mul_f32 v[80:81], v[86:87], v[96:97] op_sel_hi:[1,0]
	v_or_b32_e32 v92, 32, v158
	v_mul_f32_e32 v86, 0xbfb8aa3b, v80
	v_mul_f32_e32 v87, 0xbfb8aa3b, v81
	v_exp_f32_e32 v86, v86
	v_exp_f32_e32 v87, v87
	v_add_f32_e32 v86, 1.0, v86
	v_add_f32_e32 v87, 1.0, v87
	v_rcp_f32_e32 v86, v86
	v_rcp_f32_e32 v87, v87
	s_nop 0
	v_pk_mul_f32 v[80:81], v[80:81], v[86:87]
	s_nop 0
	v_pk_mul_f32 v[86:87], v[82:83], v[80:81]
	v_cvt_pk_bf16_f32 v82, v84, v85
	v_mad_i64_i32 v[84:85], s[26:27], v92, s17, v[112:113]
	v_lshl_add_u64 v[84:85], v[84:85], 0, s[12:13]
	v_lshl_add_u64 v[84:85], v[84:85], 0, s[68:69]
	v_cvt_pk_bf16_f32 v80, v88, v89
	v_cvt_pk_bf16_f32 v81, v90, v91
	v_cvt_pk_bf16_f32 v83, v86, v87
	v_lshl_add_u64 v[84:85], v[84:85], 0, v[146:147]
	global_store_dwordx4 v[84:85], v[80:83], off
	s_nop 1
	v_mov_b32_e32 v80, v171
	s_waitcnt lgkmcnt(0)
	v_pk_mul_f32 v[76:77], v[76:77], v[80:81] op_sel_hi:[1,0]
	s_nop 0
	v_mul_f32_e32 v81, 0xbfb8aa3b, v76
	v_exp_f32_e32 v81, v81
	s_nop 0
	v_add_f32_e32 v81, 1.0, v81
	v_rcp_f32_e32 v82, v81
	v_pk_mul_f32 v[72:73], v[72:73], v[80:81] op_sel_hi:[1,0]
	v_mul_f32_e32 v81, 0xbfb8aa3b, v77
	v_exp_f32_e32 v81, v81
	s_nop 0
	v_add_f32_e32 v81, 1.0, v81
	v_rcp_f32_e32 v83, v81
	v_pk_mul_f32 v[74:75], v[74:75], v[80:81] op_sel_hi:[1,0]
	v_pk_mul_f32 v[68:69], v[68:69], v[80:81] op_sel_hi:[1,0]
	v_pk_mul_f32 v[64:65], v[64:65], v[80:81] op_sel_hi:[1,0]
	v_pk_mul_f32 v[76:77], v[76:77], v[82:83]
	v_pk_mul_f32 v[66:67], v[66:67], v[80:81] op_sel_hi:[1,0]
	v_pk_mul_f32 v[72:73], v[72:73], v[76:77]
	v_pk_mul_f32 v[76:77], v[78:79], v[80:81] op_sel_hi:[1,0]
	s_nop 0
	v_mul_f32_e32 v78, 0xbfb8aa3b, v76
	v_mul_f32_e32 v79, 0xbfb8aa3b, v77
	v_exp_f32_e32 v78, v78
	v_exp_f32_e32 v79, v79
	v_add_f32_e32 v78, 1.0, v78
	v_add_f32_e32 v79, 1.0, v79
	v_rcp_f32_e32 v78, v78
	v_rcp_f32_e32 v79, v79
	s_nop 0
	v_pk_mul_f32 v[76:77], v[76:77], v[78:79]
	s_nop 0
	v_pk_mul_f32 v[74:75], v[74:75], v[76:77]
	v_mul_f32_e32 v76, 0xbfb8aa3b, v68
	v_mul_f32_e32 v77, 0xbfb8aa3b, v69
	v_exp_f32_e32 v76, v76
	v_exp_f32_e32 v77, v77
	v_add_f32_e32 v76, 1.0, v76
	v_add_f32_e32 v77, 1.0, v77
	v_rcp_f32_e32 v76, v76
	v_rcp_f32_e32 v77, v77
	s_nop 0
	v_pk_mul_f32 v[68:69], v[68:69], v[76:77]
	s_nop 0
	v_pk_mul_f32 v[68:69], v[64:65], v[68:69]
	v_pk_mul_f32 v[64:65], v[70:71], v[80:81] op_sel_hi:[1,0]
	v_or_b32_e32 v76, 48, v158
	v_mul_f32_e32 v70, 0xbfb8aa3b, v64
	v_mul_f32_e32 v71, 0xbfb8aa3b, v65
	v_exp_f32_e32 v70, v70
	v_exp_f32_e32 v71, v71
	v_add_f32_e32 v70, 1.0, v70
	v_add_f32_e32 v71, 1.0, v71
	v_rcp_f32_e32 v70, v70
	v_rcp_f32_e32 v71, v71
	s_nop 0
	v_pk_mul_f32 v[64:65], v[64:65], v[70:71]
	s_nop 0
	v_pk_mul_f32 v[70:71], v[66:67], v[64:65]
	v_cvt_pk_bf16_f32 v66, v68, v69
	v_mad_i64_i32 v[68:69], s[26:27], v76, s17, v[112:113]
	v_lshl_add_u64 v[68:69], v[68:69], 0, s[12:13]
	v_lshl_add_u64 v[68:69], v[68:69], 0, s[68:69]
	v_cvt_pk_bf16_f32 v64, v72, v73
	v_cvt_pk_bf16_f32 v65, v74, v75
	v_cvt_pk_bf16_f32 v67, v70, v71
	v_lshl_add_u64 v[68:69], v[68:69], 0, v[146:147]
	global_store_dwordx4 v[68:69], v[64:67], off
	s_nop 1
	v_mov_b32_e32 v64, v172
	s_nop 0
	v_add_u32_e32 v65, 0x80, v158
	s_waitcnt lgkmcnt(0)
; #define LAS __attribute__((address_space(3)))
; __device__ __forceinline__ float sigmoidf_(float x) { return __builtin_amdgcn_rcpf(1.f + __expf(-x)); }
;     __device__ __forceinline__ void operator()(const f32x4 (&acc)[2][2][4][2], const Unit& u, int wr, int wc, int fr, int fq, const LAS float* rsl) const {
;         const int row0 = u.pm * 256 + wr * 64 + fr;
; #pragma unroll
;         for (int ai = 0; ai < 2; ++ai)
; #pragma unroll
;             for (int m = 0; m < 4; ++m) {
;                 const int row = row0 + ai * 128 + m * 16; const float rs = rsl[ai * 128 + wr * 64 + m * 16 + fr];
;                 f32x4 o[2];
; #pragma unroll
;                 for (int n = 0; n < 2; ++n)
; #pragma unroll
;                     for (int j = 0; j < 4; ++j) { const float gt = acc[ai][0][m][n][j] * rs, up = acc[ai][1][m][n][j] * rs; o[n][j] = gt * sigmoidf_(gt) * up; }
;                 *(u32x4*)(ACT + (size_t)row * DFF + u.pn * 128 + wc * 32 + 8 * fq) = pack8(o[0], o[1]);
;                 asm volatile("" ::: "memory");
;             }
	v_pk_mul_f32 v[60:61], v[60:61], v[64:65] op_sel_hi:[1,0]
	s_nop 0
	v_mul_f32_e32 v66, 0xbfb8aa3b, v60
	v_mul_f32_e32 v67, 0xbfb8aa3b, v61
	v_exp_f32_e32 v66, v66
	v_exp_f32_e32 v67, v67
	v_pk_mul_f32 v[56:57], v[56:57], v[64:65] op_sel_hi:[1,0]
	v_pk_mul_f32 v[58:59], v[58:59], v[64:65] op_sel_hi:[1,0]
	v_add_f32_e32 v66, 1.0, v66
	v_add_f32_e32 v67, 1.0, v67
	v_rcp_f32_e32 v66, v66
	v_rcp_f32_e32 v67, v67
	v_pk_mul_f32 v[52:53], v[52:53], v[64:65] op_sel_hi:[1,0]
	v_pk_mul_f32 v[48:49], v[48:49], v[64:65] op_sel_hi:[1,0]
	v_pk_mul_f32 v[50:51], v[50:51], v[64:65] op_sel_hi:[1,0]
	v_pk_mul_f32 v[60:61], v[60:61], v[66:67]
	s_nop 0
	v_pk_mul_f32 v[56:57], v[56:57], v[60:61]
	v_pk_mul_f32 v[60:61], v[62:63], v[64:65] op_sel_hi:[1,0]
	s_nop 0
	v_mul_f32_e32 v62, 0xbfb8aa3b, v60
	v_mul_f32_e32 v63, 0xbfb8aa3b, v61
	v_exp_f32_e32 v62, v62
	v_exp_f32_e32 v63, v63
	v_add_f32_e32 v62, 1.0, v62
	v_add_f32_e32 v63, 1.0, v63
	v_rcp_f32_e32 v62, v62
	v_rcp_f32_e32 v63, v63
	s_nop 0
	v_pk_mul_f32 v[60:61], v[60:61], v[62:63]
	s_nop 0
	v_pk_mul_f32 v[58:59], v[58:59], v[60:61]
	v_mul_f32_e32 v60, 0xbfb8aa3b, v52
	v_mul_f32_e32 v61, 0xbfb8aa3b, v53
	v_exp_f32_e32 v60, v60
	v_exp_f32_e32 v61, v61
	v_add_f32_e32 v60, 1.0, v60
	v_add_f32_e32 v61, 1.0, v61
	v_rcp_f32_e32 v60, v60
	v_rcp_f32_e32 v61, v61
	s_nop 0
	v_pk_mul_f32 v[52:53], v[52:53], v[60:61]
	s_nop 0
	v_pk_mul_f32 v[52:53], v[48:49], v[52:53]
	v_pk_mul_f32 v[48:49], v[54:55], v[64:65] op_sel_hi:[1,0]
	s_nop 0
	v_mul_f32_e32 v54, 0xbfb8aa3b, v48
	v_mul_f32_e32 v55, 0xbfb8aa3b, v49
	v_exp_f32_e32 v54, v54
	v_exp_f32_e32 v55, v55
	v_add_f32_e32 v54, 1.0, v54
	v_add_f32_e32 v55, 1.0, v55
	v_rcp_f32_e32 v54, v54
	v_rcp_f32_e32 v55, v55
	s_nop 0
	v_pk_mul_f32 v[48:49], v[48:49], v[54:55]
	s_nop 0
	v_pk_mul_f32 v[54:55], v[50:51], v[48:49]
	v_cvt_pk_bf16_f32 v50, v52, v53
	v_mad_i64_i32 v[52:53], s[26:27], v65, s17, v[112:113]
	v_lshl_add_u64 v[52:53], v[52:53], 0, s[12:13]
	v_lshl_add_u64 v[52:53], v[52:53], 0, s[68:69]
	v_cvt_pk_bf16_f32 v48, v56, v57
	v_cvt_pk_bf16_f32 v49, v58, v59
	v_cvt_pk_bf16_f32 v51, v54, v55
	v_lshl_add_u64 v[52:53], v[52:53], 0, v[146:147]
	global_store_dwordx4 v[52:53], v[48:51], off
	s_nop 1
	v_mov_b32_e32 v48, v173
	s_waitcnt lgkmcnt(0)
	v_pk_mul_f32 v[44:45], v[44:45], v[48:49] op_sel_hi:[1,0]
	s_nop 0
	v_mul_f32_e32 v49, 0xbfb8aa3b, v44
	v_exp_f32_e32 v49, v49
	s_nop 0
	v_add_f32_e32 v49, 1.0, v49
	v_rcp_f32_e32 v50, v49
	v_pk_mul_f32 v[40:41], v[40:41], v[48:49] op_sel_hi:[1,0]
	v_mul_f32_e32 v49, 0xbfb8aa3b, v45
	v_exp_f32_e32 v49, v49
	s_nop 0
	v_add_f32_e32 v49, 1.0, v49
	v_rcp_f32_e32 v51, v49
	v_pk_mul_f32 v[42:43], v[42:43], v[48:49] op_sel_hi:[1,0]
	v_pk_mul_f32 v[36:37], v[36:37], v[48:49] op_sel_hi:[1,0]
	v_pk_mul_f32 v[32:33], v[32:33], v[48:49] op_sel_hi:[1,0]
	v_pk_mul_f32 v[44:45], v[44:45], v[50:51]
	v_pk_mul_f32 v[34:35], v[34:35], v[48:49] op_sel_hi:[1,0]
	v_pk_mul_f32 v[40:41], v[40:41], v[44:45]
	v_pk_mul_f32 v[44:45], v[46:47], v[48:49] op_sel_hi:[1,0]
	s_nop 0
	v_mul_f32_e32 v46, 0xbfb8aa3b, v44
	v_mul_f32_e32 v47, 0xbfb8aa3b, v45
	v_exp_f32_e32 v46, v46
	v_exp_f32_e32 v47, v47
	v_add_f32_e32 v46, 1.0, v46
	v_add_f32_e32 v47, 1.0, v47
	v_rcp_f32_e32 v46, v46
	v_rcp_f32_e32 v47, v47
	s_nop 0
	v_pk_mul_f32 v[44:45], v[44:45], v[46:47]
	s_nop 0
	v_pk_mul_f32 v[42:43], v[42:43], v[44:45]
	v_mul_f32_e32 v44, 0xbfb8aa3b, v36
	v_mul_f32_e32 v45, 0xbfb8aa3b, v37
	v_exp_f32_e32 v44, v44
	v_exp_f32_e32 v45, v45
	v_add_f32_e32 v44, 1.0, v44
	v_add_f32_e32 v45, 1.0, v45
	v_rcp_f32_e32 v44, v44
	v_rcp_f32_e32 v45, v45
	s_nop 0
	v_pk_mul_f32 v[36:37], v[36:37], v[44:45]
	s_nop 0
	v_pk_mul_f32 v[36:37], v[32:33], v[36:37]
	v_pk_mul_f32 v[32:33], v[38:39], v[48:49] op_sel_hi:[1,0]
	v_add_u32_e32 v44, 0x90, v158
	v_mul_f32_e32 v38, 0xbfb8aa3b, v32
	v_mul_f32_e32 v39, 0xbfb8aa3b, v33
	v_exp_f32_e32 v38, v38
	v_exp_f32_e32 v39, v39
	v_add_f32_e32 v38, 1.0, v38
	v_add_f32_e32 v39, 1.0, v39
	v_rcp_f32_e32 v38, v38
	v_rcp_f32_e32 v39, v39
	s_nop 0
	v_pk_mul_f32 v[32:33], v[32:33], v[38:39]
	s_nop 0
	v_pk_mul_f32 v[38:39], v[34:35], v[32:33]
	v_cvt_pk_bf16_f32 v34, v36, v37
	v_mad_i64_i32 v[36:37], s[26:27], v44, s17, v[112:113]
	v_lshl_add_u64 v[36:37], v[36:37], 0, s[12:13]
	v_lshl_add_u64 v[36:37], v[36:37], 0, s[68:69]
	v_cvt_pk_bf16_f32 v32, v40, v41
	v_cvt_pk_bf16_f32 v33, v42, v43
	v_cvt_pk_bf16_f32 v35, v38, v39
	v_lshl_add_u64 v[36:37], v[36:37], 0, v[146:147]
	global_store_dwordx4 v[36:37], v[32:35], off
	s_nop 1
	v_mov_b32_e32 v32, v174
	s_waitcnt lgkmcnt(0)
; #define LAS __attribute__((address_space(3)))
; __device__ __forceinline__ float sigmoidf_(float x) { return __builtin_amdgcn_rcpf(1.f + __expf(-x)); }
; #define PG8_BAR __builtin_amdgcn_s_barrier()
;     ...
;         if (!has_next) break;
; #pragma unroll
;         for (int a = 0; a < 2; ++a)
; #pragma unroll
;             for (int b = 0; b < 2; ++b)
; #pragma unroll
;                 for (int m = 0; m < 4; ++m)
; #pragma unroll
;                     for (int n = 0; n < 2; ++n) acc[a][b][m][n] = (f32x4){0.f, 0.f, 0.f, 0.f};
;         cur = nxt; cA = nA; cB = nB; ++ui;
;         if constexpr (ALIGN_EPI) { if (wr == 1) PG8_BAR; }
;     __device__ __forceinline__ void operator()(const f32x4 (&acc)[2][2][4][2], const Unit& u, int wr, int wc, int fr, int fq, const LAS float* rsl) const {
;         const int row0 = u.pm * 256 + wr * 64 + fr;
; #pragma unroll
;         for (int ai = 0; ai < 2; ++ai)
; #pragma unroll
;             for (int m = 0; m < 4; ++m) {
;                 const int row = row0 + ai * 128 + m * 16; const float rs = rsl[ai * 128 + wr * 64 + m * 16 + fr];
;                 f32x4 o[2];
; #pragma unroll
;                 for (int n = 0; n < 2; ++n)
; #pragma unroll
;                     for (int j = 0; j < 4; ++j) { const float gt = acc[ai][0][m][n][j] * rs, up = acc[ai][1][m][n][j] * rs; o[n][j] = gt * sigmoidf_(gt) * up; }
;                 *(u32x4*)(ACT + (size_t)row * DFF + u.pn * 128 + wc * 32 + 8 * fq) = pack8(o[0], o[1]);
;                 asm volatile("" ::: "memory");
;             }
	v_pk_mul_f32 v[28:29], v[28:29], v[32:33] op_sel_hi:[1,0]
	s_nop 0
	v_mul_f32_e32 v33, 0xbfb8aa3b, v28
	v_exp_f32_e32 v33, v33
	s_nop 0
	v_add_f32_e32 v33, 1.0, v33
	v_rcp_f32_e32 v34, v33
	v_pk_mul_f32 v[24:25], v[24:25], v[32:33] op_sel_hi:[1,0]
	v_mul_f32_e32 v33, 0xbfb8aa3b, v29
	v_exp_f32_e32 v33, v33
	s_nop 0
	v_add_f32_e32 v33, 1.0, v33
	v_rcp_f32_e32 v35, v33
	v_pk_mul_f32 v[26:27], v[26:27], v[32:33] op_sel_hi:[1,0]
	v_pk_mul_f32 v[20:21], v[20:21], v[32:33] op_sel_hi:[1,0]
	v_pk_mul_f32 v[16:17], v[16:17], v[32:33] op_sel_hi:[1,0]
	v_pk_mul_f32 v[28:29], v[28:29], v[34:35]
	v_pk_mul_f32 v[18:19], v[18:19], v[32:33] op_sel_hi:[1,0]
	v_pk_mul_f32 v[24:25], v[24:25], v[28:29]
	v_pk_mul_f32 v[28:29], v[30:31], v[32:33] op_sel_hi:[1,0]
	s_nop 0
	v_mul_f32_e32 v30, 0xbfb8aa3b, v28
	v_mul_f32_e32 v31, 0xbfb8aa3b, v29
	v_exp_f32_e32 v30, v30
	v_exp_f32_e32 v31, v31
	v_add_f32_e32 v30, 1.0, v30
	v_add_f32_e32 v31, 1.0, v31
	v_rcp_f32_e32 v30, v30
	v_rcp_f32_e32 v31, v31
	s_nop 0
	v_pk_mul_f32 v[28:29], v[28:29], v[30:31]
	s_nop 0
	v_pk_mul_f32 v[26:27], v[26:27], v[28:29]
	v_mul_f32_e32 v28, 0xbfb8aa3b, v20
	v_mul_f32_e32 v29, 0xbfb8aa3b, v21
	v_exp_f32_e32 v28, v28
	v_exp_f32_e32 v29, v29
	v_add_f32_e32 v28, 1.0, v28
	v_add_f32_e32 v29, 1.0, v29
	v_rcp_f32_e32 v28, v28
	v_rcp_f32_e32 v29, v29
	s_nop 0
	v_pk_mul_f32 v[20:21], v[20:21], v[28:29]
	s_nop 0
	v_pk_mul_f32 v[20:21], v[16:17], v[20:21]
	v_pk_mul_f32 v[16:17], v[22:23], v[32:33] op_sel_hi:[1,0]
	v_add_u32_e32 v28, 0xa0, v158
	v_mul_f32_e32 v22, 0xbfb8aa3b, v16
	v_mul_f32_e32 v23, 0xbfb8aa3b, v17
	v_exp_f32_e32 v22, v22
	v_exp_f32_e32 v23, v23
	v_add_f32_e32 v22, 1.0, v22
	v_add_f32_e32 v23, 1.0, v23
	v_rcp_f32_e32 v22, v22
	v_rcp_f32_e32 v23, v23
	s_nop 0
	v_pk_mul_f32 v[16:17], v[16:17], v[22:23]
	s_nop 0
	v_pk_mul_f32 v[22:23], v[18:19], v[16:17]
	v_cvt_pk_bf16_f32 v18, v20, v21
	v_mad_i64_i32 v[20:21], s[26:27], v28, s17, v[112:113]
	v_lshl_add_u64 v[20:21], v[20:21], 0, s[12:13]
	v_lshl_add_u64 v[20:21], v[20:21], 0, s[68:69]
	v_cvt_pk_bf16_f32 v16, v24, v25
	v_cvt_pk_bf16_f32 v17, v26, v27
	v_cvt_pk_bf16_f32 v19, v22, v23
	v_lshl_add_u64 v[20:21], v[20:21], 0, v[146:147]
	global_store_dwordx4 v[20:21], v[16:19], off
	s_nop 1
	v_mov_b32_e32 v16, v175
	s_waitcnt lgkmcnt(0)
	v_pk_mul_f32 v[12:13], v[12:13], v[16:17] op_sel_hi:[1,0]
	s_nop 0
	v_mul_f32_e32 v17, 0xbfb8aa3b, v12
	v_exp_f32_e32 v17, v17
	s_nop 0
	v_add_f32_e32 v17, 1.0, v17
	v_rcp_f32_e32 v18, v17
	v_pk_mul_f32 v[8:9], v[8:9], v[16:17] op_sel_hi:[1,0]
	v_mul_f32_e32 v17, 0xbfb8aa3b, v13
	v_exp_f32_e32 v17, v17
	s_nop 0
	v_add_f32_e32 v17, 1.0, v17
	v_rcp_f32_e32 v19, v17
	v_pk_mul_f32 v[10:11], v[10:11], v[16:17] op_sel_hi:[1,0]
	v_pk_mul_f32 v[4:5], v[4:5], v[16:17] op_sel_hi:[1,0]
	v_pk_mul_f32 v[0:1], v[0:1], v[16:17] op_sel_hi:[1,0]
	v_pk_mul_f32 v[12:13], v[12:13], v[18:19]
	v_pk_mul_f32 v[2:3], v[2:3], v[16:17] op_sel_hi:[1,0]
	v_pk_mul_f32 v[8:9], v[8:9], v[12:13]
	v_pk_mul_f32 v[12:13], v[14:15], v[16:17] op_sel_hi:[1,0]
	s_nop 0
	v_mul_f32_e32 v14, 0xbfb8aa3b, v12
	v_mul_f32_e32 v15, 0xbfb8aa3b, v13
	v_exp_f32_e32 v14, v14
	v_exp_f32_e32 v15, v15
	v_add_f32_e32 v14, 1.0, v14
	v_add_f32_e32 v15, 1.0, v15
	v_rcp_f32_e32 v14, v14
	v_rcp_f32_e32 v15, v15
	s_nop 0
	v_pk_mul_f32 v[12:13], v[12:13], v[14:15]
	s_nop 0
	v_pk_mul_f32 v[10:11], v[10:11], v[12:13]
	v_mul_f32_e32 v12, 0xbfb8aa3b, v4
	v_mul_f32_e32 v13, 0xbfb8aa3b, v5
	v_exp_f32_e32 v12, v12
	v_exp_f32_e32 v13, v13
	v_add_f32_e32 v12, 1.0, v12
	v_add_f32_e32 v13, 1.0, v13
	v_rcp_f32_e32 v12, v12
	v_rcp_f32_e32 v13, v13
	s_nop 0
	v_pk_mul_f32 v[4:5], v[4:5], v[12:13]
	s_nop 0
	v_pk_mul_f32 v[4:5], v[0:1], v[4:5]
	v_pk_mul_f32 v[0:1], v[6:7], v[16:17] op_sel_hi:[1,0]
	v_add_u32_e32 v12, 0xb0, v158
	v_mul_f32_e32 v6, 0xbfb8aa3b, v0
	v_mul_f32_e32 v7, 0xbfb8aa3b, v1
	v_exp_f32_e32 v6, v6
	v_exp_f32_e32 v7, v7
	v_add_f32_e32 v6, 1.0, v6
	v_add_f32_e32 v7, 1.0, v7
	v_rcp_f32_e32 v6, v6
	v_rcp_f32_e32 v7, v7
	s_nop 0
	v_pk_mul_f32 v[0:1], v[0:1], v[6:7]
	s_nop 0
	v_pk_mul_f32 v[6:7], v[2:3], v[0:1]
	v_cvt_pk_bf16_f32 v2, v4, v5
	v_mad_i64_i32 v[4:5], s[26:27], v12, s17, v[112:113]
	v_lshl_add_u64 v[4:5], v[4:5], 0, s[12:13]
	v_lshl_add_u64 v[4:5], v[4:5], 0, s[68:69]
	v_cvt_pk_bf16_f32 v0, v8, v9
	v_cvt_pk_bf16_f32 v1, v10, v11
	v_cvt_pk_bf16_f32 v3, v6, v7
	v_lshl_add_u64 v[4:5], v[4:5], 0, v[146:147]
	global_store_dwordx4 v[4:5], v[0:3], off
	s_mov_b64 s[12:13], -1
	s_cbranch_vccnz .LBB0_197
	s_andn2_b64 vcc, exec, s[4:5]
	s_cbranch_vccnz .LBB0_196
	s_barrier
	s_branch .LBB0_196

; #define LAS __attribute__((address_space(3)))
; __device__ __forceinline__ float sigmoidf_(float x) { return __builtin_amdgcn_rcpf(1.f + __expf(-x)); }
;     __device__ __forceinline__ void operator()(const f32x4 (&acc)[2][2][4][2], const Unit& u, int wr, int wc, int fr, int fq, const LAS float* rsl) const {
;         const int row0 = u.pm * 256 + wr * 64 + fr;
; #pragma unroll
;         for (int ai = 0; ai < 2; ++ai)
; #pragma unroll
;             for (int m = 0; m < 4; ++m) {
;                 const int row = row0 + ai * 128 + m * 16; const float rs = rsl[ai * 128 + wr * 64 + m * 16 + fr];
; #pragma unroll
;                 for (int bj = 0; bj < 2; ++bj) {
;                     f32x4 v0 = acc[ai][bj][m][0] * rs, v1 = acc[ai][bj][m][1] * rs;
; #pragma unroll
;                     for (int j = 0; j < 4; ++j) { v0[j] = sigmoidf_(v0[j]); v1[j] = sigmoidf_(v1[j]); }
;                     *(u32x4*)(P + (size_t)row * PW + u.pn * 256 + bj * 128 + wc * 32 + 8 * fq) = pack8(v0, v1);
;                 }
;                 asm volatile("" ::: "memory");
;             }
;     }
.LBB0_348:
	v_add_u32_e32 v158, s51, v156
	ds_read_b32 v168, v158
	ds_read_b32 v169, v158 offset:64
	ds_read_b32 v170, v158 offset:128
	ds_read_b32 v171, v158 offset:192
	ds_read_b32 v172, v158 offset:512
	ds_read_b32 v173, v158 offset:576
	ds_read_b32 v174, v158 offset:640
	ds_read_b32 v175, v158 offset:704
	s_waitcnt lgkmcnt(0)
	s_nop 1
	v_mov_b32_e32 v160, v168
	s_lshl_b32 s12, s50, 8
	v_lshl_add_u32 v159, s24, 8, v142
	s_ashr_i32 s13, s12, 31
	s_lshl_b64 s[12:13], s[12:13], 1
	s_waitcnt lgkmcnt(0)
	v_pk_mul_f32 v[124:125], v[124:125], v[160:161] op_sel_hi:[1,0]
	v_pk_mul_f32 v[120:121], v[120:121], v[160:161] op_sel_hi:[1,0]
	v_pk_mul_f32 v[122:123], v[122:123], v[160:161] op_sel_hi:[1,0]
	v_pk_mul_f32 v[126:127], v[126:127], v[160:161] op_sel_hi:[1,0]
	v_mul_f32_e32 v124, 0xbfb8aa3b, v124
	v_mul_f32_e32 v120, 0xbfb8aa3b, v120
	v_mul_f32_e32 v125, 0xbfb8aa3b, v125
	v_mul_f32_e32 v121, 0xbfb8aa3b, v121
	v_mul_f32_e32 v122, 0xbfb8aa3b, v122
	v_exp_f32_e32 v124, v124
	v_exp_f32_e32 v120, v120
	v_exp_f32_e32 v125, v125
	v_exp_f32_e32 v121, v121
	v_mul_f32_e32 v126, 0xbfb8aa3b, v126
	v_exp_f32_e32 v122, v122
	v_mul_f32_e32 v127, 0xbfb8aa3b, v127
	v_exp_f32_e32 v126, v126
	v_exp_f32_e32 v127, v127
	v_mul_f32_e32 v123, 0xbfb8aa3b, v123
	v_add_f32_e32 v124, 1.0, v124
	v_add_f32_e32 v120, 1.0, v120
	v_add_f32_e32 v125, 1.0, v125
	v_add_f32_e32 v121, 1.0, v121
	v_add_f32_e32 v122, 1.0, v122
	v_exp_f32_e32 v123, v123
	v_rcp_f32_e32 v124, v124
	v_rcp_f32_e32 v120, v120
	v_rcp_f32_e32 v125, v125
	v_rcp_f32_e32 v121, v121
	v_add_f32_e32 v126, 1.0, v126
	v_rcp_f32_e32 v152, v122
	v_add_f32_e32 v122, 1.0, v127
	v_rcp_f32_e32 v126, v126
	v_rcp_f32_e32 v127, v122
	v_pk_mul_f32 v[112:113], v[112:113], v[160:161] op_sel_hi:[1,0]
	v_add_f32_e32 v122, 1.0, v123
	v_pk_mul_f32 v[116:117], v[116:117], v[160:161] op_sel_hi:[1,0]
	v_mul_f32_e32 v112, 0xbfb8aa3b, v112
	v_rcp_f32_e32 v153, v122
	v_cvt_pk_bf16_f32 v122, v124, v125
	v_cvt_pk_bf16_f32 v124, v120, v121
	v_mov_b64_e32 v[120:121], s[72:73]
	v_exp_f32_e32 v112, v112
	v_mul_f32_e32 v117, 0xbfb8aa3b, v117
	v_cvt_pk_bf16_f32 v123, v126, v127
	v_mad_i64_i32 v[126:127], s[26:27], v159, s80, v[120:121]
	v_exp_f32_e32 v117, v117
	v_lshl_add_u64 v[126:127], v[126:127], 0, s[12:13]
	v_lshl_add_u64 v[126:127], v[126:127], 0, s[68:69]
	v_cvt_pk_bf16_f32 v125, v152, v153
	v_lshl_add_u64 v[126:127], v[126:127], 0, v[146:147]
	v_pk_mul_f32 v[118:119], v[118:119], v[160:161] op_sel_hi:[1,0]
	v_add_f32_e32 v112, 1.0, v112
	v_mul_f32_e32 v113, 0xbfb8aa3b, v113
	global_store_dwordx4 v[126:127], v[122:125], off
	v_exp_f32_e32 v113, v113
	v_pk_mul_f32 v[114:115], v[114:115], v[160:161] op_sel_hi:[1,0]
	v_rcp_f32_e32 v122, v112
	v_add_f32_e32 v112, 1.0, v117
	v_mul_f32_e32 v117, 0xbfb8aa3b, v118
	v_exp_f32_e32 v117, v117
	v_add_f32_e32 v113, 1.0, v113
	v_mul_f32_e32 v114, 0xbfb8aa3b, v114
	v_mul_f32_e32 v116, 0xbfb8aa3b, v116
	v_exp_f32_e32 v114, v114
	v_rcp_f32_e32 v118, v113
	v_add_f32_e32 v113, 1.0, v117
	v_mul_f32_e32 v117, 0xbfb8aa3b, v119
	v_mul_f32_e32 v115, 0xbfb8aa3b, v115
	v_exp_f32_e32 v116, v116
	v_exp_f32_e32 v117, v117
	v_exp_f32_e32 v115, v115
	v_add_f32_e32 v114, 1.0, v114
	v_add_f32_e32 v116, 1.0, v116
	v_rcp_f32_e32 v119, v114
	v_add_f32_e32 v114, 1.0, v117
	v_add_f32_e32 v115, 1.0, v115
	v_rcp_f32_e32 v116, v116
	v_rcp_f32_e32 v112, v112
	v_rcp_f32_e32 v113, v113
	v_rcp_f32_e32 v114, v114
	v_rcp_f32_e32 v115, v115
	v_cvt_pk_bf16_f32 v112, v116, v112
	s_and_b64 vcc, exec, s[10:11]
	v_cvt_pk_bf16_f32 v113, v113, v114
	v_cvt_pk_bf16_f32 v114, v122, v118
	v_cvt_pk_bf16_f32 v115, v119, v115
	global_store_dwordx4 v[126:127], v[112:115], off offset:256
	s_nop 1
	v_mov_b32_e32 v112, v169
	s_mov_b64 s[10:11], -1
	v_or_b32_e32 v113, 16, v159
	s_waitcnt lgkmcnt(0)
	v_pk_mul_f32 v[104:105], v[104:105], v[112:113] op_sel_hi:[1,0]
	v_pk_mul_f32 v[108:109], v[108:109], v[112:113] op_sel_hi:[1,0]
	v_mul_f32_e32 v104, 0xbfb8aa3b, v104
	v_exp_f32_e32 v104, v104
	v_mul_f32_e32 v109, 0xbfb8aa3b, v109
	v_exp_f32_e32 v109, v109
	v_pk_mul_f32 v[110:111], v[110:111], v[112:113] op_sel_hi:[1,0]
	v_add_f32_e32 v104, 1.0, v104
	v_mul_f32_e32 v105, 0xbfb8aa3b, v105
	v_exp_f32_e32 v105, v105
	v_rcp_f32_e32 v114, v104
	v_add_f32_e32 v104, 1.0, v109
	v_mul_f32_e32 v109, 0xbfb8aa3b, v110
	v_exp_f32_e32 v109, v109
	v_mul_f32_e32 v108, 0xbfb8aa3b, v108
	v_exp_f32_e32 v108, v108
	v_pk_mul_f32 v[106:107], v[106:107], v[112:113] op_sel_hi:[1,0]
	v_add_f32_e32 v105, 1.0, v105
	v_mul_f32_e32 v106, 0xbfb8aa3b, v106
	v_exp_f32_e32 v106, v106
	v_rcp_f32_e32 v110, v105
	v_add_f32_e32 v105, 1.0, v109
	v_mul_f32_e32 v109, 0xbfb8aa3b, v111
	v_mul_f32_e32 v107, 0xbfb8aa3b, v107
	v_exp_f32_e32 v109, v109
	v_exp_f32_e32 v107, v107
	v_add_f32_e32 v108, 1.0, v108
	v_rcp_f32_e32 v108, v108
	v_rcp_f32_e32 v104, v104
	v_add_f32_e32 v106, 1.0, v106
	v_pk_mul_f32 v[96:97], v[96:97], v[112:113] op_sel_hi:[1,0]
	v_rcp_f32_e32 v111, v106
	v_add_f32_e32 v106, 1.0, v109
	v_add_f32_e32 v107, 1.0, v107
	v_pk_mul_f32 v[100:101], v[100:101], v[112:113] op_sel_hi:[1,0]
	v_mul_f32_e32 v96, 0xbfb8aa3b, v96
	v_rcp_f32_e32 v105, v105
	v_rcp_f32_e32 v106, v106
	v_rcp_f32_e32 v107, v107
	v_exp_f32_e32 v96, v96
	v_mul_f32_e32 v101, 0xbfb8aa3b, v101
	v_cvt_pk_bf16_f32 v104, v108, v104
	v_mad_i64_i32 v[108:109], s[26:27], v113, s80, v[120:121]
	v_exp_f32_e32 v101, v101
	v_lshl_add_u64 v[108:109], v[108:109], 0, s[12:13]
	v_lshl_add_u64 v[108:109], v[108:109], 0, s[68:69]
	v_cvt_pk_bf16_f32 v105, v105, v106
	v_cvt_pk_bf16_f32 v106, v114, v110
	v_cvt_pk_bf16_f32 v107, v111, v107
	v_lshl_add_u64 v[108:109], v[108:109], 0, v[146:147]
	v_pk_mul_f32 v[102:103], v[102:103], v[112:113] op_sel_hi:[1,0]
	v_add_f32_e32 v96, 1.0, v96
	v_mul_f32_e32 v97, 0xbfb8aa3b, v97
	global_store_dwordx4 v[108:109], v[104:107], off
	v_exp_f32_e32 v97, v97
	v_pk_mul_f32 v[98:99], v[98:99], v[112:113] op_sel_hi:[1,0]
	v_rcp_f32_e32 v104, v96
	v_add_f32_e32 v96, 1.0, v101
	v_mul_f32_e32 v101, 0xbfb8aa3b, v102
	v_exp_f32_e32 v101, v101
	v_add_f32_e32 v97, 1.0, v97
	v_mul_f32_e32 v98, 0xbfb8aa3b, v98
	v_mul_f32_e32 v100, 0xbfb8aa3b, v100
	v_exp_f32_e32 v98, v98
	v_rcp_f32_e32 v102, v97
	v_add_f32_e32 v97, 1.0, v101
	v_mul_f32_e32 v101, 0xbfb8aa3b, v103
	v_mul_f32_e32 v99, 0xbfb8aa3b, v99
	v_exp_f32_e32 v100, v100
	v_exp_f32_e32 v101, v101
	v_exp_f32_e32 v99, v99
	v_add_f32_e32 v98, 1.0, v98
	v_add_f32_e32 v100, 1.0, v100
	v_rcp_f32_e32 v103, v98
	v_add_f32_e32 v98, 1.0, v101
	v_add_f32_e32 v99, 1.0, v99
	v_rcp_f32_e32 v100, v100
	v_rcp_f32_e32 v96, v96
	v_rcp_f32_e32 v97, v97
	v_rcp_f32_e32 v98, v98
	v_rcp_f32_e32 v99, v99
	v_cvt_pk_bf16_f32 v96, v100, v96
	v_cvt_pk_bf16_f32 v97, v97, v98
	v_cvt_pk_bf16_f32 v98, v104, v102
	v_cvt_pk_bf16_f32 v99, v103, v99
	global_store_dwordx4 v[108:109], v[96:99], off offset:256
	s_nop 1
	v_mov_b32_e32 v96, v170
	s_nop 0
	v_or_b32_e32 v97, 32, v159
	s_waitcnt lgkmcnt(0)
; #define LAS __attribute__((address_space(3)))
; __device__ __forceinline__ float sigmoidf_(float x) { return __builtin_amdgcn_rcpf(1.f + __expf(-x)); }
;     __device__ __forceinline__ void operator()(const f32x4 (&acc)[2][2][4][2], const Unit& u, int wr, int wc, int fr, int fq, const LAS float* rsl) const {
;         const int row0 = u.pm * 256 + wr * 64 + fr;
; #pragma unroll
;         for (int ai = 0; ai < 2; ++ai)
; #pragma unroll
;             for (int m = 0; m < 4; ++m) {
;                 const int row = row0 + ai * 128 + m * 16; const float rs = rsl[ai * 128 + wr * 64 + m * 16 + fr];
; #pragma unroll
;                 for (int bj = 0; bj < 2; ++bj) {
;                     f32x4 v0 = acc[ai][bj][m][0] * rs, v1 = acc[ai][bj][m][1] * rs;
; #pragma unroll
;                     for (int j = 0; j < 4; ++j) { v0[j] = sigmoidf_(v0[j]); v1[j] = sigmoidf_(v1[j]); }
;                     *(u32x4*)(P + (size_t)row * PW + u.pn * 256 + bj * 128 + wc * 32 + 8 * fq) = pack8(v0, v1);
;                 }
;                 asm volatile("" ::: "memory");
;             }
;     }
	v_pk_mul_f32 v[88:89], v[88:89], v[96:97] op_sel_hi:[1,0]
	v_pk_mul_f32 v[92:93], v[92:93], v[96:97] op_sel_hi:[1,0]
	v_mul_f32_e32 v88, 0xbfb8aa3b, v88
	v_exp_f32_e32 v88, v88
	v_mul_f32_e32 v93, 0xbfb8aa3b, v93
	v_exp_f32_e32 v93, v93
	v_pk_mul_f32 v[94:95], v[94:95], v[96:97] op_sel_hi:[1,0]
	v_add_f32_e32 v88, 1.0, v88
	v_mul_f32_e32 v89, 0xbfb8aa3b, v89
	v_exp_f32_e32 v89, v89
	v_rcp_f32_e32 v98, v88
	v_add_f32_e32 v88, 1.0, v93
	v_mul_f32_e32 v93, 0xbfb8aa3b, v94
	v_exp_f32_e32 v93, v93
	v_mul_f32_e32 v92, 0xbfb8aa3b, v92
	v_exp_f32_e32 v92, v92
	v_pk_mul_f32 v[90:91], v[90:91], v[96:97] op_sel_hi:[1,0]
	v_add_f32_e32 v89, 1.0, v89
	v_mul_f32_e32 v90, 0xbfb8aa3b, v90
	v_exp_f32_e32 v90, v90
	v_rcp_f32_e32 v94, v89
	v_add_f32_e32 v89, 1.0, v93
	v_mul_f32_e32 v93, 0xbfb8aa3b, v95
	v_mul_f32_e32 v91, 0xbfb8aa3b, v91
	v_exp_f32_e32 v93, v93
	v_exp_f32_e32 v91, v91
	v_add_f32_e32 v92, 1.0, v92
	v_rcp_f32_e32 v92, v92
	v_rcp_f32_e32 v88, v88
	v_add_f32_e32 v90, 1.0, v90
	v_pk_mul_f32 v[80:81], v[80:81], v[96:97] op_sel_hi:[1,0]
	v_rcp_f32_e32 v95, v90
	v_add_f32_e32 v90, 1.0, v93
	v_add_f32_e32 v91, 1.0, v91
	v_pk_mul_f32 v[84:85], v[84:85], v[96:97] op_sel_hi:[1,0]
	v_mul_f32_e32 v80, 0xbfb8aa3b, v80
	v_rcp_f32_e32 v89, v89
	v_rcp_f32_e32 v90, v90
	v_rcp_f32_e32 v91, v91
	v_exp_f32_e32 v80, v80
	v_mul_f32_e32 v85, 0xbfb8aa3b, v85
	v_cvt_pk_bf16_f32 v88, v92, v88
	v_mad_i64_i32 v[92:93], s[26:27], v97, s80, v[120:121]
	v_exp_f32_e32 v85, v85
	v_lshl_add_u64 v[92:93], v[92:93], 0, s[12:13]
	v_lshl_add_u64 v[92:93], v[92:93], 0, s[68:69]
	v_cvt_pk_bf16_f32 v89, v89, v90
	v_cvt_pk_bf16_f32 v90, v98, v94
	v_cvt_pk_bf16_f32 v91, v95, v91
	v_lshl_add_u64 v[92:93], v[92:93], 0, v[146:147]
	v_pk_mul_f32 v[86:87], v[86:87], v[96:97] op_sel_hi:[1,0]
	v_add_f32_e32 v80, 1.0, v80
	v_mul_f32_e32 v81, 0xbfb8aa3b, v81
	global_store_dwordx4 v[92:93], v[88:91], off
	v_exp_f32_e32 v81, v81
	v_pk_mul_f32 v[82:83], v[82:83], v[96:97] op_sel_hi:[1,0]
	v_rcp_f32_e32 v88, v80
	v_add_f32_e32 v80, 1.0, v85
	v_mul_f32_e32 v85, 0xbfb8aa3b, v86
	v_exp_f32_e32 v85, v85
	v_add_f32_e32 v81, 1.0, v81
	v_mul_f32_e32 v82, 0xbfb8aa3b, v82
	v_mul_f32_e32 v84, 0xbfb8aa3b, v84
	v_exp_f32_e32 v82, v82
	v_rcp_f32_e32 v86, v81
	v_add_f32_e32 v81, 1.0, v85
	v_mul_f32_e32 v85, 0xbfb8aa3b, v87
	v_mul_f32_e32 v83, 0xbfb8aa3b, v83
	v_exp_f32_e32 v84, v84
	v_exp_f32_e32 v85, v85
	v_exp_f32_e32 v83, v83
	v_add_f32_e32 v82, 1.0, v82
	v_add_f32_e32 v84, 1.0, v84
	v_rcp_f32_e32 v87, v82
	v_add_f32_e32 v82, 1.0, v85
	v_add_f32_e32 v83, 1.0, v83
	v_rcp_f32_e32 v84, v84
	v_rcp_f32_e32 v80, v80
	v_rcp_f32_e32 v81, v81
	v_rcp_f32_e32 v82, v82
	v_rcp_f32_e32 v83, v83
	v_cvt_pk_bf16_f32 v80, v84, v80
	v_cvt_pk_bf16_f32 v81, v81, v82
	v_cvt_pk_bf16_f32 v82, v88, v86
	v_cvt_pk_bf16_f32 v83, v87, v83
	global_store_dwordx4 v[92:93], v[80:83], off offset:256
	s_nop 1
	v_mov_b32_e32 v80, v171
	s_nop 0
	v_or_b32_e32 v81, 48, v159
	s_waitcnt lgkmcnt(0)
	v_pk_mul_f32 v[72:73], v[72:73], v[80:81] op_sel_hi:[1,0]
	v_pk_mul_f32 v[76:77], v[76:77], v[80:81] op_sel_hi:[1,0]
	v_mul_f32_e32 v72, 0xbfb8aa3b, v72
	v_exp_f32_e32 v72, v72
	v_mul_f32_e32 v77, 0xbfb8aa3b, v77
	v_exp_f32_e32 v77, v77
	v_pk_mul_f32 v[78:79], v[78:79], v[80:81] op_sel_hi:[1,0]
	v_add_f32_e32 v72, 1.0, v72
	v_mul_f32_e32 v73, 0xbfb8aa3b, v73
	v_exp_f32_e32 v73, v73
	v_rcp_f32_e32 v82, v72
	v_add_f32_e32 v72, 1.0, v77
	v_mul_f32_e32 v77, 0xbfb8aa3b, v78
	v_exp_f32_e32 v77, v77
	v_mul_f32_e32 v76, 0xbfb8aa3b, v76
	v_exp_f32_e32 v76, v76
	v_pk_mul_f32 v[74:75], v[74:75], v[80:81] op_sel_hi:[1,0]
	v_add_f32_e32 v73, 1.0, v73
	v_mul_f32_e32 v74, 0xbfb8aa3b, v74
	v_exp_f32_e32 v74, v74
	v_rcp_f32_e32 v78, v73
	v_add_f32_e32 v73, 1.0, v77
	v_mul_f32_e32 v77, 0xbfb8aa3b, v79
	v_mul_f32_e32 v75, 0xbfb8aa3b, v75
	v_exp_f32_e32 v77, v77
	v_exp_f32_e32 v75, v75
	v_add_f32_e32 v76, 1.0, v76
	v_rcp_f32_e32 v76, v76
	v_rcp_f32_e32 v72, v72
	v_add_f32_e32 v74, 1.0, v74
	v_pk_mul_f32 v[64:65], v[64:65], v[80:81] op_sel_hi:[1,0]
	v_rcp_f32_e32 v79, v74
	v_add_f32_e32 v74, 1.0, v77
	v_add_f32_e32 v75, 1.0, v75
	v_pk_mul_f32 v[68:69], v[68:69], v[80:81] op_sel_hi:[1,0]
	v_mul_f32_e32 v64, 0xbfb8aa3b, v64
	v_rcp_f32_e32 v73, v73
	v_rcp_f32_e32 v74, v74
	v_rcp_f32_e32 v75, v75
	v_exp_f32_e32 v64, v64
	v_mul_f32_e32 v69, 0xbfb8aa3b, v69
	v_cvt_pk_bf16_f32 v72, v76, v72
	v_mad_i64_i32 v[76:77], s[26:27], v81, s80, v[120:121]
	v_exp_f32_e32 v69, v69
	v_lshl_add_u64 v[76:77], v[76:77], 0, s[12:13]
	v_lshl_add_u64 v[76:77], v[76:77], 0, s[68:69]
	v_cvt_pk_bf16_f32 v73, v73, v74
	v_cvt_pk_bf16_f32 v74, v82, v78
	v_cvt_pk_bf16_f32 v75, v79, v75
	v_lshl_add_u64 v[76:77], v[76:77], 0, v[146:147]
	v_pk_mul_f32 v[70:71], v[70:71], v[80:81] op_sel_hi:[1,0]
	v_add_f32_e32 v64, 1.0, v64
	v_mul_f32_e32 v65, 0xbfb8aa3b, v65
	global_store_dwordx4 v[76:77], v[72:75], off
	v_exp_f32_e32 v65, v65
	v_pk_mul_f32 v[66:67], v[66:67], v[80:81] op_sel_hi:[1,0]
	v_rcp_f32_e32 v72, v64
	v_add_f32_e32 v64, 1.0, v69
	v_mul_f32_e32 v69, 0xbfb8aa3b, v70
	v_exp_f32_e32 v69, v69
	v_add_f32_e32 v65, 1.0, v65
	v_mul_f32_e32 v66, 0xbfb8aa3b, v66
	v_mul_f32_e32 v68, 0xbfb8aa3b, v68
	v_exp_f32_e32 v66, v66
	v_rcp_f32_e32 v70, v65
	v_add_f32_e32 v65, 1.0, v69
	v_mul_f32_e32 v69, 0xbfb8aa3b, v71
	v_mul_f32_e32 v67, 0xbfb8aa3b, v67
	v_exp_f32_e32 v68, v68
	v_exp_f32_e32 v69, v69
	v_exp_f32_e32 v67, v67
	v_add_f32_e32 v66, 1.0, v66
	v_add_f32_e32 v68, 1.0, v68
	v_rcp_f32_e32 v71, v66
	v_add_f32_e32 v66, 1.0, v69
	v_add_f32_e32 v67, 1.0, v67
	v_rcp_f32_e32 v68, v68
	v_rcp_f32_e32 v64, v64
	v_rcp_f32_e32 v65, v65
	v_rcp_f32_e32 v66, v66
	v_rcp_f32_e32 v67, v67
	v_cvt_pk_bf16_f32 v64, v68, v64
	v_cvt_pk_bf16_f32 v65, v65, v66
	v_cvt_pk_bf16_f32 v66, v72, v70
	v_cvt_pk_bf16_f32 v67, v71, v67
	global_store_dwordx4 v[76:77], v[64:67], off offset:256
	s_nop 1
	v_mov_b32_e32 v64, v172
	s_nop 0
	v_add_u32_e32 v65, 0x80, v159
	s_waitcnt lgkmcnt(0)
; #define LAS __attribute__((address_space(3)))
; __device__ __forceinline__ float sigmoidf_(float x) { return __builtin_amdgcn_rcpf(1.f + __expf(-x)); }
;     __device__ __forceinline__ void operator()(const f32x4 (&acc)[2][2][4][2], const Unit& u, int wr, int wc, int fr, int fq, const LAS float* rsl) const {
;         const int row0 = u.pm * 256 + wr * 64 + fr;
; #pragma unroll
;         for (int ai = 0; ai < 2; ++ai)
; #pragma unroll
;             for (int m = 0; m < 4; ++m) {
;                 const int row = row0 + ai * 128 + m * 16; const float rs = rsl[ai * 128 + wr * 64 + m * 16 + fr];
; #pragma unroll
;                 for (int bj = 0; bj < 2; ++bj) {
;                     f32x4 v0 = acc[ai][bj][m][0] * rs, v1 = acc[ai][bj][m][1] * rs;
; #pragma unroll
;                     for (int j = 0; j < 4; ++j) { v0[j] = sigmoidf_(v0[j]); v1[j] = sigmoidf_(v1[j]); }
;                     *(u32x4*)(P + (size_t)row * PW + u.pn * 256 + bj * 128 + wc * 32 + 8 * fq) = pack8(v0, v1);
;                 }
;                 asm volatile("" ::: "memory");
;             }
;     }
	v_pk_mul_f32 v[56:57], v[56:57], v[64:65] op_sel_hi:[1,0]
	v_pk_mul_f32 v[60:61], v[60:61], v[64:65] op_sel_hi:[1,0]
	v_mul_f32_e32 v56, 0xbfb8aa3b, v56
	v_exp_f32_e32 v56, v56
	v_mul_f32_e32 v61, 0xbfb8aa3b, v61
	v_exp_f32_e32 v61, v61
	v_pk_mul_f32 v[62:63], v[62:63], v[64:65] op_sel_hi:[1,0]
	v_add_f32_e32 v56, 1.0, v56
	v_mul_f32_e32 v57, 0xbfb8aa3b, v57
	v_exp_f32_e32 v57, v57
	v_rcp_f32_e32 v66, v56
	v_add_f32_e32 v56, 1.0, v61
	v_mul_f32_e32 v61, 0xbfb8aa3b, v62
	v_exp_f32_e32 v61, v61
	v_mul_f32_e32 v60, 0xbfb8aa3b, v60
	v_exp_f32_e32 v60, v60
	v_pk_mul_f32 v[58:59], v[58:59], v[64:65] op_sel_hi:[1,0]
	v_add_f32_e32 v57, 1.0, v57
	v_mul_f32_e32 v58, 0xbfb8aa3b, v58
	v_exp_f32_e32 v58, v58
	v_rcp_f32_e32 v62, v57
	v_add_f32_e32 v57, 1.0, v61
	v_mul_f32_e32 v61, 0xbfb8aa3b, v63
	v_mul_f32_e32 v59, 0xbfb8aa3b, v59
	v_exp_f32_e32 v61, v61
	v_exp_f32_e32 v59, v59
	v_add_f32_e32 v60, 1.0, v60
	v_rcp_f32_e32 v60, v60
	v_rcp_f32_e32 v56, v56
	v_add_f32_e32 v58, 1.0, v58
	v_pk_mul_f32 v[48:49], v[48:49], v[64:65] op_sel_hi:[1,0]
	v_rcp_f32_e32 v63, v58
	v_add_f32_e32 v58, 1.0, v61
	v_add_f32_e32 v59, 1.0, v59
	v_pk_mul_f32 v[52:53], v[52:53], v[64:65] op_sel_hi:[1,0]
	v_mul_f32_e32 v48, 0xbfb8aa3b, v48
	v_rcp_f32_e32 v57, v57
	v_rcp_f32_e32 v58, v58
	v_rcp_f32_e32 v59, v59
	v_exp_f32_e32 v48, v48
	v_mul_f32_e32 v53, 0xbfb8aa3b, v53
	v_cvt_pk_bf16_f32 v56, v60, v56
	v_mad_i64_i32 v[60:61], s[26:27], v65, s80, v[120:121]
	v_exp_f32_e32 v53, v53
	v_lshl_add_u64 v[60:61], v[60:61], 0, s[12:13]
	v_lshl_add_u64 v[60:61], v[60:61], 0, s[68:69]
	v_cvt_pk_bf16_f32 v57, v57, v58
	v_cvt_pk_bf16_f32 v58, v66, v62
	v_cvt_pk_bf16_f32 v59, v63, v59
	v_lshl_add_u64 v[60:61], v[60:61], 0, v[146:147]
	v_pk_mul_f32 v[54:55], v[54:55], v[64:65] op_sel_hi:[1,0]
	v_add_f32_e32 v48, 1.0, v48
	v_mul_f32_e32 v49, 0xbfb8aa3b, v49
	global_store_dwordx4 v[60:61], v[56:59], off
	v_exp_f32_e32 v49, v49
	v_pk_mul_f32 v[50:51], v[50:51], v[64:65] op_sel_hi:[1,0]
	v_rcp_f32_e32 v56, v48
	v_add_f32_e32 v48, 1.0, v53
	v_mul_f32_e32 v53, 0xbfb8aa3b, v54
	v_exp_f32_e32 v53, v53
	v_add_f32_e32 v49, 1.0, v49
	v_mul_f32_e32 v50, 0xbfb8aa3b, v50
	v_mul_f32_e32 v52, 0xbfb8aa3b, v52
	v_exp_f32_e32 v50, v50
	v_rcp_f32_e32 v54, v49
	v_add_f32_e32 v49, 1.0, v53
	v_mul_f32_e32 v53, 0xbfb8aa3b, v55
	v_mul_f32_e32 v51, 0xbfb8aa3b, v51
	v_exp_f32_e32 v52, v52
	v_exp_f32_e32 v53, v53
	v_exp_f32_e32 v51, v51
	v_add_f32_e32 v50, 1.0, v50
	v_add_f32_e32 v52, 1.0, v52
	v_rcp_f32_e32 v55, v50
	v_add_f32_e32 v50, 1.0, v53
	v_add_f32_e32 v51, 1.0, v51
	v_rcp_f32_e32 v52, v52
	v_rcp_f32_e32 v48, v48
	v_rcp_f32_e32 v49, v49
	v_rcp_f32_e32 v50, v50
	v_rcp_f32_e32 v51, v51
	v_cvt_pk_bf16_f32 v48, v52, v48
	v_cvt_pk_bf16_f32 v49, v49, v50
	v_cvt_pk_bf16_f32 v50, v56, v54
	v_cvt_pk_bf16_f32 v51, v55, v51
	global_store_dwordx4 v[60:61], v[48:51], off offset:256
	s_nop 1
	v_mov_b32_e32 v48, v173
	s_nop 0
	v_add_u32_e32 v49, 0x90, v159
	s_waitcnt lgkmcnt(0)
	v_pk_mul_f32 v[40:41], v[40:41], v[48:49] op_sel_hi:[1,0]
	v_pk_mul_f32 v[44:45], v[44:45], v[48:49] op_sel_hi:[1,0]
	v_mul_f32_e32 v40, 0xbfb8aa3b, v40
	v_exp_f32_e32 v40, v40
	v_mul_f32_e32 v45, 0xbfb8aa3b, v45
	v_exp_f32_e32 v45, v45
	v_pk_mul_f32 v[46:47], v[46:47], v[48:49] op_sel_hi:[1,0]
	v_add_f32_e32 v40, 1.0, v40
	v_mul_f32_e32 v41, 0xbfb8aa3b, v41
	v_exp_f32_e32 v41, v41
	v_rcp_f32_e32 v50, v40
	v_add_f32_e32 v40, 1.0, v45
	v_mul_f32_e32 v45, 0xbfb8aa3b, v46
	v_exp_f32_e32 v45, v45
	v_mul_f32_e32 v44, 0xbfb8aa3b, v44
	v_exp_f32_e32 v44, v44
	v_pk_mul_f32 v[42:43], v[42:43], v[48:49] op_sel_hi:[1,0]
	v_add_f32_e32 v41, 1.0, v41
	v_mul_f32_e32 v42, 0xbfb8aa3b, v42
	v_exp_f32_e32 v42, v42
	v_rcp_f32_e32 v46, v41
	v_add_f32_e32 v41, 1.0, v45
	v_mul_f32_e32 v45, 0xbfb8aa3b, v47
	v_mul_f32_e32 v43, 0xbfb8aa3b, v43
	v_exp_f32_e32 v45, v45
	v_exp_f32_e32 v43, v43
	v_add_f32_e32 v44, 1.0, v44
	v_rcp_f32_e32 v44, v44
	v_rcp_f32_e32 v40, v40
	v_add_f32_e32 v42, 1.0, v42
	v_pk_mul_f32 v[32:33], v[32:33], v[48:49] op_sel_hi:[1,0]
	v_rcp_f32_e32 v47, v42
	v_add_f32_e32 v42, 1.0, v45
	v_add_f32_e32 v43, 1.0, v43
	v_pk_mul_f32 v[36:37], v[36:37], v[48:49] op_sel_hi:[1,0]
	v_mul_f32_e32 v32, 0xbfb8aa3b, v32
	v_rcp_f32_e32 v41, v41
	v_rcp_f32_e32 v42, v42
	v_rcp_f32_e32 v43, v43
	v_exp_f32_e32 v32, v32
	v_mul_f32_e32 v37, 0xbfb8aa3b, v37
	v_cvt_pk_bf16_f32 v40, v44, v40
	v_mad_i64_i32 v[44:45], s[26:27], v49, s80, v[120:121]
	v_exp_f32_e32 v37, v37
	v_lshl_add_u64 v[44:45], v[44:45], 0, s[12:13]
	v_lshl_add_u64 v[44:45], v[44:45], 0, s[68:69]
	v_cvt_pk_bf16_f32 v41, v41, v42
	v_cvt_pk_bf16_f32 v42, v50, v46
	v_cvt_pk_bf16_f32 v43, v47, v43
	v_lshl_add_u64 v[44:45], v[44:45], 0, v[146:147]
	v_pk_mul_f32 v[38:39], v[38:39], v[48:49] op_sel_hi:[1,0]
	v_add_f32_e32 v32, 1.0, v32
	v_mul_f32_e32 v33, 0xbfb8aa3b, v33
	global_store_dwordx4 v[44:45], v[40:43], off
	v_exp_f32_e32 v33, v33
	v_pk_mul_f32 v[34:35], v[34:35], v[48:49] op_sel_hi:[1,0]
	v_rcp_f32_e32 v40, v32
	v_add_f32_e32 v32, 1.0, v37
	v_mul_f32_e32 v37, 0xbfb8aa3b, v38
	v_exp_f32_e32 v37, v37
	v_add_f32_e32 v33, 1.0, v33
	v_mul_f32_e32 v34, 0xbfb8aa3b, v34
	v_mul_f32_e32 v36, 0xbfb8aa3b, v36
	v_exp_f32_e32 v34, v34
	v_rcp_f32_e32 v38, v33
	v_add_f32_e32 v33, 1.0, v37
	v_mul_f32_e32 v37, 0xbfb8aa3b, v39
	v_mul_f32_e32 v35, 0xbfb8aa3b, v35
	v_exp_f32_e32 v36, v36
	v_exp_f32_e32 v37, v37
	v_exp_f32_e32 v35, v35
	v_add_f32_e32 v34, 1.0, v34
	v_add_f32_e32 v36, 1.0, v36
	v_rcp_f32_e32 v39, v34
	v_add_f32_e32 v34, 1.0, v37
	v_add_f32_e32 v35, 1.0, v35
	v_rcp_f32_e32 v36, v36
	v_rcp_f32_e32 v32, v32
	v_rcp_f32_e32 v33, v33
	v_rcp_f32_e32 v34, v34
	v_rcp_f32_e32 v35, v35
	v_cvt_pk_bf16_f32 v32, v36, v32
	v_cvt_pk_bf16_f32 v33, v33, v34
	v_cvt_pk_bf16_f32 v34, v40, v38
	v_cvt_pk_bf16_f32 v35, v39, v35
	global_store_dwordx4 v[44:45], v[32:35], off offset:256
	s_nop 1
	v_mov_b32_e32 v32, v174
	s_nop 0
	v_add_u32_e32 v33, 0xa0, v159
	s_waitcnt lgkmcnt(0)
; #define LAS __attribute__((address_space(3)))
; __device__ __forceinline__ float sigmoidf_(float x) { return __builtin_amdgcn_rcpf(1.f + __expf(-x)); }
; #define PG8_BAR __builtin_amdgcn_s_barrier()
;     ...
;         if (!has_next) break;
; #pragma unroll
;         for (int a = 0; a < 2; ++a)
; #pragma unroll
;             for (int b = 0; b < 2; ++b)
; #pragma unroll
;                 for (int m = 0; m < 4; ++m)
; #pragma unroll
;                     for (int n = 0; n < 2; ++n) acc[a][b][m][n] = (f32x4){0.f, 0.f, 0.f, 0.f};
;         cur = nxt; cA = nA; cB = nB; ++ui;
;         if constexpr (ALIGN_EPI) { if (wr == 1) PG8_BAR; }
;     __device__ __forceinline__ void operator()(const f32x4 (&acc)[2][2][4][2], const Unit& u, int wr, int wc, int fr, int fq, const LAS float* rsl) const {
;         const int row0 = u.pm * 256 + wr * 64 + fr;
; #pragma unroll
;         for (int ai = 0; ai < 2; ++ai)
; #pragma unroll
;             for (int m = 0; m < 4; ++m) {
;                 const int row = row0 + ai * 128 + m * 16; const float rs = rsl[ai * 128 + wr * 64 + m * 16 + fr];
; #pragma unroll
;                 for (int bj = 0; bj < 2; ++bj) {
;                     f32x4 v0 = acc[ai][bj][m][0] * rs, v1 = acc[ai][bj][m][1] * rs;
; #pragma unroll
;                     for (int j = 0; j < 4; ++j) { v0[j] = sigmoidf_(v0[j]); v1[j] = sigmoidf_(v1[j]); }
;                     *(u32x4*)(P + (size_t)row * PW + u.pn * 256 + bj * 128 + wc * 32 + 8 * fq) = pack8(v0, v1);
;                 }
;                 asm volatile("" ::: "memory");
;             }
;     }
	v_pk_mul_f32 v[24:25], v[24:25], v[32:33] op_sel_hi:[1,0]
	v_pk_mul_f32 v[28:29], v[28:29], v[32:33] op_sel_hi:[1,0]
	v_mul_f32_e32 v24, 0xbfb8aa3b, v24
	v_exp_f32_e32 v24, v24
	v_mul_f32_e32 v29, 0xbfb8aa3b, v29
	v_exp_f32_e32 v29, v29
	v_pk_mul_f32 v[30:31], v[30:31], v[32:33] op_sel_hi:[1,0]
	v_add_f32_e32 v24, 1.0, v24
	v_mul_f32_e32 v25, 0xbfb8aa3b, v25
	v_exp_f32_e32 v25, v25
	v_rcp_f32_e32 v34, v24
	v_add_f32_e32 v24, 1.0, v29
	v_mul_f32_e32 v29, 0xbfb8aa3b, v30
	v_exp_f32_e32 v29, v29
	v_mul_f32_e32 v28, 0xbfb8aa3b, v28
	v_exp_f32_e32 v28, v28
	v_pk_mul_f32 v[26:27], v[26:27], v[32:33] op_sel_hi:[1,0]
	v_add_f32_e32 v25, 1.0, v25
	v_mul_f32_e32 v26, 0xbfb8aa3b, v26
	v_exp_f32_e32 v26, v26
	v_rcp_f32_e32 v30, v25
	v_add_f32_e32 v25, 1.0, v29
	v_mul_f32_e32 v29, 0xbfb8aa3b, v31
	v_mul_f32_e32 v27, 0xbfb8aa3b, v27
	v_exp_f32_e32 v29, v29
	v_exp_f32_e32 v27, v27
	v_add_f32_e32 v28, 1.0, v28
	v_rcp_f32_e32 v28, v28
	v_rcp_f32_e32 v24, v24
	v_add_f32_e32 v26, 1.0, v26
	v_pk_mul_f32 v[16:17], v[16:17], v[32:33] op_sel_hi:[1,0]
	v_rcp_f32_e32 v31, v26
	v_add_f32_e32 v26, 1.0, v29
	v_add_f32_e32 v27, 1.0, v27
	v_pk_mul_f32 v[20:21], v[20:21], v[32:33] op_sel_hi:[1,0]
	v_mul_f32_e32 v16, 0xbfb8aa3b, v16
	v_rcp_f32_e32 v25, v25
	v_rcp_f32_e32 v26, v26
	v_rcp_f32_e32 v27, v27
	v_exp_f32_e32 v16, v16
	v_mul_f32_e32 v21, 0xbfb8aa3b, v21
	v_cvt_pk_bf16_f32 v24, v28, v24
	v_mad_i64_i32 v[28:29], s[26:27], v33, s80, v[120:121]
	v_exp_f32_e32 v21, v21
	v_lshl_add_u64 v[28:29], v[28:29], 0, s[12:13]
	v_lshl_add_u64 v[28:29], v[28:29], 0, s[68:69]
	v_cvt_pk_bf16_f32 v25, v25, v26
	v_cvt_pk_bf16_f32 v26, v34, v30
	v_cvt_pk_bf16_f32 v27, v31, v27
	v_lshl_add_u64 v[28:29], v[28:29], 0, v[146:147]
	v_pk_mul_f32 v[22:23], v[22:23], v[32:33] op_sel_hi:[1,0]
	v_add_f32_e32 v16, 1.0, v16
	v_mul_f32_e32 v17, 0xbfb8aa3b, v17
	global_store_dwordx4 v[28:29], v[24:27], off
	v_exp_f32_e32 v17, v17
	v_pk_mul_f32 v[18:19], v[18:19], v[32:33] op_sel_hi:[1,0]
	v_rcp_f32_e32 v24, v16
	v_add_f32_e32 v16, 1.0, v21
	v_mul_f32_e32 v21, 0xbfb8aa3b, v22
	v_exp_f32_e32 v21, v21
	v_add_f32_e32 v17, 1.0, v17
	v_mul_f32_e32 v18, 0xbfb8aa3b, v18
	v_mul_f32_e32 v20, 0xbfb8aa3b, v20
	v_exp_f32_e32 v18, v18
	v_rcp_f32_e32 v22, v17
	v_add_f32_e32 v17, 1.0, v21
	v_mul_f32_e32 v21, 0xbfb8aa3b, v23
	v_mul_f32_e32 v19, 0xbfb8aa3b, v19
	v_exp_f32_e32 v20, v20
	v_exp_f32_e32 v21, v21
	v_exp_f32_e32 v19, v19
	v_add_f32_e32 v18, 1.0, v18
	v_add_f32_e32 v20, 1.0, v20
	v_rcp_f32_e32 v23, v18
	v_add_f32_e32 v18, 1.0, v21
	v_add_f32_e32 v19, 1.0, v19
	v_rcp_f32_e32 v20, v20
	v_rcp_f32_e32 v16, v16
	v_rcp_f32_e32 v17, v17
	v_rcp_f32_e32 v18, v18
	v_rcp_f32_e32 v19, v19
	v_cvt_pk_bf16_f32 v16, v20, v16
	v_cvt_pk_bf16_f32 v17, v17, v18
	v_cvt_pk_bf16_f32 v18, v24, v22
	v_cvt_pk_bf16_f32 v19, v23, v19
	global_store_dwordx4 v[28:29], v[16:19], off offset:256
	s_nop 1
	v_mov_b32_e32 v16, v175
	s_nop 0
	v_add_u32_e32 v17, 0xb0, v159
	s_waitcnt lgkmcnt(0)
	v_pk_mul_f32 v[8:9], v[8:9], v[16:17] op_sel_hi:[1,0]
	v_pk_mul_f32 v[12:13], v[12:13], v[16:17] op_sel_hi:[1,0]
	v_mul_f32_e32 v8, 0xbfb8aa3b, v8
	v_exp_f32_e32 v8, v8
	v_mul_f32_e32 v13, 0xbfb8aa3b, v13
	v_exp_f32_e32 v13, v13
	v_pk_mul_f32 v[14:15], v[14:15], v[16:17] op_sel_hi:[1,0]
	v_add_f32_e32 v8, 1.0, v8
	v_mul_f32_e32 v9, 0xbfb8aa3b, v9
	v_exp_f32_e32 v9, v9
	v_rcp_f32_e32 v18, v8
	v_add_f32_e32 v8, 1.0, v13
	v_mul_f32_e32 v13, 0xbfb8aa3b, v14
	v_exp_f32_e32 v13, v13
	v_mul_f32_e32 v12, 0xbfb8aa3b, v12
	v_exp_f32_e32 v12, v12
	v_pk_mul_f32 v[10:11], v[10:11], v[16:17] op_sel_hi:[1,0]
	v_add_f32_e32 v9, 1.0, v9
	v_mul_f32_e32 v10, 0xbfb8aa3b, v10
	v_exp_f32_e32 v10, v10
	v_rcp_f32_e32 v14, v9
	v_add_f32_e32 v9, 1.0, v13
	v_mul_f32_e32 v13, 0xbfb8aa3b, v15
	v_mul_f32_e32 v11, 0xbfb8aa3b, v11
	v_exp_f32_e32 v13, v13
	v_exp_f32_e32 v11, v11
	v_add_f32_e32 v12, 1.0, v12
	v_rcp_f32_e32 v12, v12
	v_rcp_f32_e32 v8, v8
	v_add_f32_e32 v10, 1.0, v10
	v_pk_mul_f32 v[0:1], v[0:1], v[16:17] op_sel_hi:[1,0]
	v_rcp_f32_e32 v15, v10
	v_add_f32_e32 v10, 1.0, v13
	v_add_f32_e32 v11, 1.0, v11
	v_pk_mul_f32 v[4:5], v[4:5], v[16:17] op_sel_hi:[1,0]
	v_mul_f32_e32 v0, 0xbfb8aa3b, v0
	v_rcp_f32_e32 v9, v9
	v_rcp_f32_e32 v10, v10
	v_rcp_f32_e32 v11, v11
	v_exp_f32_e32 v0, v0
	v_mul_f32_e32 v5, 0xbfb8aa3b, v5
	v_cvt_pk_bf16_f32 v8, v12, v8
	v_mad_i64_i32 v[12:13], s[26:27], v17, s80, v[120:121]
	v_exp_f32_e32 v5, v5
	v_lshl_add_u64 v[12:13], v[12:13], 0, s[12:13]
	v_lshl_add_u64 v[12:13], v[12:13], 0, s[68:69]
	v_cvt_pk_bf16_f32 v9, v9, v10
	v_cvt_pk_bf16_f32 v10, v18, v14
	v_cvt_pk_bf16_f32 v11, v15, v11
	v_lshl_add_u64 v[12:13], v[12:13], 0, v[146:147]
	v_pk_mul_f32 v[6:7], v[6:7], v[16:17] op_sel_hi:[1,0]
	v_add_f32_e32 v0, 1.0, v0
	v_mul_f32_e32 v1, 0xbfb8aa3b, v1
	global_store_dwordx4 v[12:13], v[8:11], off
	v_exp_f32_e32 v1, v1
	v_pk_mul_f32 v[2:3], v[2:3], v[16:17] op_sel_hi:[1,0]
	v_rcp_f32_e32 v8, v0
	v_add_f32_e32 v0, 1.0, v5
	v_mul_f32_e32 v5, 0xbfb8aa3b, v6
	v_exp_f32_e32 v5, v5
	v_add_f32_e32 v1, 1.0, v1
	v_mul_f32_e32 v2, 0xbfb8aa3b, v2
	v_mul_f32_e32 v4, 0xbfb8aa3b, v4
	v_exp_f32_e32 v2, v2
	v_rcp_f32_e32 v6, v1
	v_add_f32_e32 v1, 1.0, v5
	v_mul_f32_e32 v5, 0xbfb8aa3b, v7
	v_mul_f32_e32 v3, 0xbfb8aa3b, v3
	v_exp_f32_e32 v4, v4
	v_exp_f32_e32 v5, v5
	v_exp_f32_e32 v3, v3
	v_add_f32_e32 v2, 1.0, v2
	v_add_f32_e32 v4, 1.0, v4
	v_rcp_f32_e32 v7, v2
	v_add_f32_e32 v2, 1.0, v5
	v_add_f32_e32 v3, 1.0, v3
	v_rcp_f32_e32 v4, v4
	v_rcp_f32_e32 v0, v0
	v_rcp_f32_e32 v1, v1
	v_rcp_f32_e32 v2, v2
	v_rcp_f32_e32 v3, v3
	v_cvt_pk_bf16_f32 v0, v4, v0
	v_cvt_pk_bf16_f32 v1, v1, v2
	v_cvt_pk_bf16_f32 v2, v8, v6
	v_cvt_pk_bf16_f32 v3, v7, v3
	global_store_dwordx4 v[12:13], v[0:3], off offset:256
	s_cbranch_vccnz .LBB0_332
	s_andn2_b64 vcc, exec, s[4:5]
	s_cbranch_vccnz .LBB0_331
	s_barrier
	s_branch .LBB0_331

; #define LAS __attribute__((address_space(3)))
; __device__ __forceinline__ float bflo(unsigned w) { return __uint_as_float(w << 16); }
; __device__ __forceinline__ float bfhi(unsigned w) { return __uint_as_float(w & 0xffff0000u); }
;     __device__ __forceinline__ void operator()(const f32x4 (&acc)[2][2][4][2], const Unit& u, int wr, int wc, int fr, int fq, const LAS float* rsl) const {
;         const int row0 = u.pm * 256 + wr * 64 + fr;
; #pragma unroll
;         for (int ai = 0; ai < 2; ++ai)
; #pragma unroll
;             for (int m = 0; m < 4; ++m) {
;                 const int row = row0 + ai * 128 + m * 16; const float rs = rsl[ai * 128 + wr * 64 + m * 16 + fr];
;                 if (u.pn < 14) {
; #pragma unroll
;                     for (int bj = 0; bj < 2; ++bj) {
;                         const f32x4 v0 = acc[ai][bj][m][0] * rs, v1 = acc[ai][bj][m][1] * rs;
;                         *(u32x4*)(P + (size_t)row * PW + u.pn * 256 + bj * 128 + wc * 32 + 8 * fq) = pack8(v0, v1);
;                     }
;                 } else if (wc == 0) {
;                     const f32x4 v0 = acc[ai][0][m][0] * rs, v1 = acc[ai][0][m][1] * rs;
;                     const u32x4 hi = pack8(v0, v1);
;                     const f32x4 d0 = (f32x4){v0[0] - bflo(hi.x), v0[1] - bfhi(hi.x), v0[2] - bflo(hi.y), v0[3] - bfhi(hi.y)};
;                     const f32x4 d1 = (f32x4){v1[0] - bflo(hi.z), v1[1] - bfhi(hi.z), v1[2] - bflo(hi.w), v1[3] - bfhi(hi.w)};
;                     bf16_t* lp = lr + (size_t)row * 64 + (fq >> 1) * 32 + (fq & 1) * 8;
;                     *(u32x4*)lp = hi; *(u32x4*)(lp + 16) = pack8(d0, d1);
;                 }
;             }
;     }
.LBB0_556:
	v_add_u32_e32 v164, s15, v162
	ds_read_b32 v184, v164
	ds_read_b32 v185, v164 offset:64
	ds_read_b32 v186, v164 offset:128
	ds_read_b32 v187, v164 offset:192
	ds_read_b32 v188, v164 offset:512
	ds_read_b32 v189, v164 offset:576
	ds_read_b32 v190, v164 offset:640
	ds_read_b32 v191, v164 offset:704
	s_waitcnt lgkmcnt(0)
	s_nop 1
	v_mov_b32_e32 v160, v184
	s_cmp_gt_i32 s50, 13
	s_cselect_b64 s[28:29], -1, 0
	v_cndmask_b32_e64 v146, 0, 1, s[18:19]
	v_lshl_add_u32 v158, s14, 8, v137
	s_mov_b64 s[14:15], -1
	s_and_b64 vcc, exec, s[28:29]
	v_cmp_ne_u32_e64 s[12:13], 1, v146
	s_cbranch_vccz .LBB0_560
	s_and_b64 vcc, exec, s[12:13]
	s_cbranch_vccnz .LBB0_559
	s_waitcnt lgkmcnt(0)
	v_pk_mul_f32 v[168:169], v[126:127], v[160:161] op_sel_hi:[1,0]
	v_pk_mul_f32 v[166:167], v[124:125], v[160:161] op_sel_hi:[1,0]
	v_pk_mul_f32 v[170:171], v[122:123], v[160:161] op_sel_hi:[1,0]
	v_pk_mul_f32 v[172:173], v[120:121], v[160:161] op_sel_hi:[1,0]
	v_cvt_pk_bf16_f32 v166, v166, v167
	v_cvt_pk_bf16_f32 v167, v168, v169
	v_cvt_pk_bf16_f32 v168, v172, v173
	v_cvt_pk_bf16_f32 v169, v170, v171
	v_ashrrev_i32_e32 v159, 31, v158
	v_lshlrev_b32_e32 v170, 16, v166
	v_and_b32_e32 v171, 0xffff0000, v166
	v_lshlrev_b32_e32 v172, 16, v167
	v_and_b32_e32 v173, 0xffff0000, v167
	v_lshlrev_b32_e32 v174, 16, v168
	v_and_b32_e32 v175, 0xffff0000, v168
	v_lshlrev_b32_e32 v176, 16, v169
	v_and_b32_e32 v177, 0xffff0000, v169
	v_lshlrev_b64 v[178:179], 7, v[158:159]
	v_pk_fma_f32 v[170:171], v[124:125], v[160:161], v[170:171] op_sel_hi:[1,0,1] neg_lo:[0,0,1] neg_hi:[0,0,1]
	v_pk_fma_f32 v[172:173], v[126:127], v[160:161], v[172:173] op_sel_hi:[1,0,1] neg_lo:[0,0,1] neg_hi:[0,0,1]
	v_pk_fma_f32 v[174:175], v[120:121], v[160:161], v[174:175] op_sel_hi:[1,0,1] neg_lo:[0,0,1] neg_hi:[0,0,1]
	v_pk_fma_f32 v[176:177], v[122:123], v[160:161], v[176:177] op_sel_hi:[1,0,1] neg_lo:[0,0,1] neg_hi:[0,0,1]
	v_lshl_add_u64 v[178:179], v[140:141], 0, v[178:179]
	global_store_dwordx4 v[178:179], v[166:169], off
	s_nop 1
	v_cvt_pk_bf16_f32 v166, v170, v171
	v_cvt_pk_bf16_f32 v167, v172, v173
	v_cvt_pk_bf16_f32 v168, v174, v175
	v_cvt_pk_bf16_f32 v169, v176, v177
	global_store_dwordx4 v[178:179], v[166:169], off offset:32

; #define LAS __attribute__((address_space(3)))
; __device__ __forceinline__ float bflo(unsigned w) { return __uint_as_float(w << 16); }
; __device__ __forceinline__ float bfhi(unsigned w) { return __uint_as_float(w & 0xffff0000u); }
;     __device__ __forceinline__ void operator()(const f32x4 (&acc)[2][2][4][2], const Unit& u, int wr, int wc, int fr, int fq, const LAS float* rsl) const {
;         const int row0 = u.pm * 256 + wr * 64 + fr;
; #pragma unroll
;         for (int ai = 0; ai < 2; ++ai)
; #pragma unroll
;             for (int m = 0; m < 4; ++m) {
;                 const int row = row0 + ai * 128 + m * 16; const float rs = rsl[ai * 128 + wr * 64 + m * 16 + fr];
;                 if (u.pn < 14) {
; #pragma unroll
;                     for (int bj = 0; bj < 2; ++bj) {
;                         const f32x4 v0 = acc[ai][bj][m][0] * rs, v1 = acc[ai][bj][m][1] * rs;
;                         *(u32x4*)(P + (size_t)row * PW + u.pn * 256 + bj * 128 + wc * 32 + 8 * fq) = pack8(v0, v1);
;                     }
;                 } else if (wc == 0) {
;                     const f32x4 v0 = acc[ai][0][m][0] * rs, v1 = acc[ai][0][m][1] * rs;
;                     const u32x4 hi = pack8(v0, v1);
;                     const f32x4 d0 = (f32x4){v0[0] - bflo(hi.x), v0[1] - bfhi(hi.x), v0[2] - bflo(hi.y), v0[3] - bfhi(hi.y)};
;                     const f32x4 d1 = (f32x4){v1[0] - bflo(hi.z), v1[1] - bfhi(hi.z), v1[2] - bflo(hi.w), v1[3] - bfhi(hi.w)};
;                     bf16_t* lp = lr + (size_t)row * 64 + (fq >> 1) * 32 + (fq & 1) * 8;
;                     *(u32x4*)lp = hi; *(u32x4*)(lp + 16) = pack8(d0, d1);
;                 }
;             }
;     }
.LBB0_562:
	s_nop 1
	v_mov_b32_e32 v112, v185
	s_nop 0
	v_cndmask_b32_e64 v113, 0, 1, s[28:29]
	v_or_b32_e32 v114, 16, v158
	v_cmp_ne_u32_e64 s[14:15], 1, v113
	s_andn2_b64 vcc, exec, s[28:29]
	s_mov_b64 s[28:29], -1
	s_cbranch_vccnz .LBB0_566
	s_and_b64 vcc, exec, s[12:13]
	s_cbranch_vccnz .LBB0_565
	s_waitcnt lgkmcnt(0)
	v_pk_mul_f32 v[118:119], v[110:111], v[112:113] op_sel_hi:[1,0]
	v_pk_mul_f32 v[116:117], v[108:109], v[112:113] op_sel_hi:[1,0]
	v_pk_mul_f32 v[120:121], v[106:107], v[112:113] op_sel_hi:[1,0]
	v_pk_mul_f32 v[122:123], v[104:105], v[112:113] op_sel_hi:[1,0]
	v_cvt_pk_bf16_f32 v116, v116, v117
	v_cvt_pk_bf16_f32 v117, v118, v119
	v_cvt_pk_bf16_f32 v118, v122, v123
	v_cvt_pk_bf16_f32 v119, v120, v121
	v_ashrrev_i32_e32 v115, 31, v114
	v_lshlrev_b32_e32 v120, 16, v116
	v_and_b32_e32 v121, 0xffff0000, v116
	v_lshlrev_b32_e32 v122, 16, v117
	v_and_b32_e32 v123, 0xffff0000, v117
	v_lshlrev_b32_e32 v124, 16, v118
	v_and_b32_e32 v125, 0xffff0000, v118
	v_lshlrev_b32_e32 v126, 16, v119
	v_and_b32_e32 v127, 0xffff0000, v119
	v_lshlrev_b64 v[166:167], 7, v[114:115]
	v_pk_fma_f32 v[120:121], v[108:109], v[112:113], v[120:121] op_sel_hi:[1,0,1] neg_lo:[0,0,1] neg_hi:[0,0,1]
	v_pk_fma_f32 v[122:123], v[110:111], v[112:113], v[122:123] op_sel_hi:[1,0,1] neg_lo:[0,0,1] neg_hi:[0,0,1]
	v_pk_fma_f32 v[124:125], v[104:105], v[112:113], v[124:125] op_sel_hi:[1,0,1] neg_lo:[0,0,1] neg_hi:[0,0,1]
	v_pk_fma_f32 v[126:127], v[106:107], v[112:113], v[126:127] op_sel_hi:[1,0,1] neg_lo:[0,0,1] neg_hi:[0,0,1]
	v_lshl_add_u64 v[166:167], v[140:141], 0, v[166:167]
	global_store_dwordx4 v[166:167], v[116:119], off
	s_nop 1
	v_cvt_pk_bf16_f32 v116, v120, v121
	v_cvt_pk_bf16_f32 v117, v122, v123
	v_cvt_pk_bf16_f32 v118, v124, v125
	v_cvt_pk_bf16_f32 v119, v126, v127
	global_store_dwordx4 v[166:167], v[116:119], off offset:32

; #define LAS __attribute__((address_space(3)))
; __device__ __forceinline__ float bflo(unsigned w) { return __uint_as_float(w << 16); }
; __device__ __forceinline__ float bfhi(unsigned w) { return __uint_as_float(w & 0xffff0000u); }
;     __device__ __forceinline__ void operator()(const f32x4 (&acc)[2][2][4][2], const Unit& u, int wr, int wc, int fr, int fq, const LAS float* rsl) const {
;         const int row0 = u.pm * 256 + wr * 64 + fr;
; #pragma unroll
;         for (int ai = 0; ai < 2; ++ai)
; #pragma unroll
;             for (int m = 0; m < 4; ++m) {
;                 const int row = row0 + ai * 128 + m * 16; const float rs = rsl[ai * 128 + wr * 64 + m * 16 + fr];
;                 if (u.pn < 14) {
; #pragma unroll
;                     for (int bj = 0; bj < 2; ++bj) {
;                         const f32x4 v0 = acc[ai][bj][m][0] * rs, v1 = acc[ai][bj][m][1] * rs;
;                         *(u32x4*)(P + (size_t)row * PW + u.pn * 256 + bj * 128 + wc * 32 + 8 * fq) = pack8(v0, v1);
;                     }
;                 } else if (wc == 0) {
;                     const f32x4 v0 = acc[ai][0][m][0] * rs, v1 = acc[ai][0][m][1] * rs;
;                     const u32x4 hi = pack8(v0, v1);
;                     const f32x4 d0 = (f32x4){v0[0] - bflo(hi.x), v0[1] - bfhi(hi.x), v0[2] - bflo(hi.y), v0[3] - bfhi(hi.y)};
;                     const f32x4 d1 = (f32x4){v1[0] - bflo(hi.z), v1[1] - bfhi(hi.z), v1[2] - bflo(hi.w), v1[3] - bfhi(hi.w)};
;                     bf16_t* lp = lr + (size_t)row * 64 + (fq >> 1) * 32 + (fq & 1) * 8;
;                     *(u32x4*)lp = hi; *(u32x4*)(lp + 16) = pack8(d0, d1);
;                 }
;             }
;     }
.LBB0_568:
	s_nop 1
	v_mov_b32_e32 v96, v186
	s_nop 0
	v_or_b32_e32 v98, 32, v158
	s_and_b64 vcc, exec, s[14:15]
	s_mov_b64 s[28:29], -1
	s_cbranch_vccnz .LBB0_572
	s_and_b64 vcc, exec, s[12:13]
	s_cbranch_vccnz .LBB0_571
	s_waitcnt lgkmcnt(0)
	v_pk_mul_f32 v[102:103], v[94:95], v[96:97] op_sel_hi:[1,0]
	v_pk_mul_f32 v[100:101], v[92:93], v[96:97] op_sel_hi:[1,0]
	v_pk_mul_f32 v[104:105], v[90:91], v[96:97] op_sel_hi:[1,0]
	v_pk_mul_f32 v[106:107], v[88:89], v[96:97] op_sel_hi:[1,0]
	v_cvt_pk_bf16_f32 v100, v100, v101
	v_cvt_pk_bf16_f32 v101, v102, v103
	v_cvt_pk_bf16_f32 v102, v106, v107
	v_cvt_pk_bf16_f32 v103, v104, v105
	v_ashrrev_i32_e32 v99, 31, v98
	v_lshlrev_b32_e32 v104, 16, v100
	v_and_b32_e32 v105, 0xffff0000, v100
	v_lshlrev_b32_e32 v106, 16, v101
	v_and_b32_e32 v107, 0xffff0000, v101
	v_lshlrev_b32_e32 v108, 16, v102
	v_and_b32_e32 v109, 0xffff0000, v102
	v_lshlrev_b32_e32 v110, 16, v103
	v_and_b32_e32 v111, 0xffff0000, v103
	v_lshlrev_b64 v[112:113], 7, v[98:99]
	v_pk_fma_f32 v[104:105], v[92:93], v[96:97], v[104:105] op_sel_hi:[1,0,1] neg_lo:[0,0,1] neg_hi:[0,0,1]
	v_pk_fma_f32 v[106:107], v[94:95], v[96:97], v[106:107] op_sel_hi:[1,0,1] neg_lo:[0,0,1] neg_hi:[0,0,1]
	v_pk_fma_f32 v[108:109], v[88:89], v[96:97], v[108:109] op_sel_hi:[1,0,1] neg_lo:[0,0,1] neg_hi:[0,0,1]
	v_pk_fma_f32 v[110:111], v[90:91], v[96:97], v[110:111] op_sel_hi:[1,0,1] neg_lo:[0,0,1] neg_hi:[0,0,1]
	v_lshl_add_u64 v[112:113], v[140:141], 0, v[112:113]
	global_store_dwordx4 v[112:113], v[100:103], off
	s_nop 1
	v_cvt_pk_bf16_f32 v100, v104, v105
	v_cvt_pk_bf16_f32 v101, v106, v107
	v_cvt_pk_bf16_f32 v102, v108, v109
	v_cvt_pk_bf16_f32 v103, v110, v111
	global_store_dwordx4 v[112:113], v[100:103], off offset:32

; #define LAS __attribute__((address_space(3)))
; __device__ __forceinline__ float bflo(unsigned w) { return __uint_as_float(w << 16); }
; __device__ __forceinline__ float bfhi(unsigned w) { return __uint_as_float(w & 0xffff0000u); }
;     __device__ __forceinline__ void operator()(const f32x4 (&acc)[2][2][4][2], const Unit& u, int wr, int wc, int fr, int fq, const LAS float* rsl) const {
;         const int row0 = u.pm * 256 + wr * 64 + fr;
; #pragma unroll
;         for (int ai = 0; ai < 2; ++ai)
; #pragma unroll
;             for (int m = 0; m < 4; ++m) {
;                 const int row = row0 + ai * 128 + m * 16; const float rs = rsl[ai * 128 + wr * 64 + m * 16 + fr];
;                 if (u.pn < 14) {
; #pragma unroll
;                     for (int bj = 0; bj < 2; ++bj) {
;                         const f32x4 v0 = acc[ai][bj][m][0] * rs, v1 = acc[ai][bj][m][1] * rs;
;                         *(u32x4*)(P + (size_t)row * PW + u.pn * 256 + bj * 128 + wc * 32 + 8 * fq) = pack8(v0, v1);
;                     }
;                 } else if (wc == 0) {
;                     const f32x4 v0 = acc[ai][0][m][0] * rs, v1 = acc[ai][0][m][1] * rs;
;                     const u32x4 hi = pack8(v0, v1);
;                     const f32x4 d0 = (f32x4){v0[0] - bflo(hi.x), v0[1] - bfhi(hi.x), v0[2] - bflo(hi.y), v0[3] - bfhi(hi.y)};
;                     const f32x4 d1 = (f32x4){v1[0] - bflo(hi.z), v1[1] - bfhi(hi.z), v1[2] - bflo(hi.w), v1[3] - bfhi(hi.w)};
;                     bf16_t* lp = lr + (size_t)row * 64 + (fq >> 1) * 32 + (fq & 1) * 8;
;                     *(u32x4*)lp = hi; *(u32x4*)(lp + 16) = pack8(d0, d1);
;                 }
;             }
;     }
.LBB0_574:
	s_nop 1
	v_mov_b32_e32 v80, v187
	s_nop 0
	v_or_b32_e32 v82, 48, v158
	s_and_b64 vcc, exec, s[14:15]
	s_mov_b64 s[28:29], -1
	s_cbranch_vccnz .LBB0_578
	s_and_b64 vcc, exec, s[12:13]
	s_cbranch_vccnz .LBB0_577
	s_waitcnt lgkmcnt(0)
	v_pk_mul_f32 v[86:87], v[78:79], v[80:81] op_sel_hi:[1,0]
	v_pk_mul_f32 v[84:85], v[76:77], v[80:81] op_sel_hi:[1,0]
	v_pk_mul_f32 v[88:89], v[74:75], v[80:81] op_sel_hi:[1,0]
	v_pk_mul_f32 v[90:91], v[72:73], v[80:81] op_sel_hi:[1,0]
	v_cvt_pk_bf16_f32 v84, v84, v85
	v_cvt_pk_bf16_f32 v85, v86, v87
	v_cvt_pk_bf16_f32 v86, v90, v91
	v_cvt_pk_bf16_f32 v87, v88, v89
	v_ashrrev_i32_e32 v83, 31, v82
	v_lshlrev_b32_e32 v88, 16, v84
	v_and_b32_e32 v89, 0xffff0000, v84
	v_lshlrev_b32_e32 v90, 16, v85
	v_and_b32_e32 v91, 0xffff0000, v85
	v_lshlrev_b32_e32 v92, 16, v86
	v_and_b32_e32 v93, 0xffff0000, v86
	v_lshlrev_b32_e32 v94, 16, v87
	v_and_b32_e32 v95, 0xffff0000, v87
	v_lshlrev_b64 v[96:97], 7, v[82:83]
	v_pk_fma_f32 v[88:89], v[76:77], v[80:81], v[88:89] op_sel_hi:[1,0,1] neg_lo:[0,0,1] neg_hi:[0,0,1]
	v_pk_fma_f32 v[90:91], v[78:79], v[80:81], v[90:91] op_sel_hi:[1,0,1] neg_lo:[0,0,1] neg_hi:[0,0,1]
	v_pk_fma_f32 v[92:93], v[72:73], v[80:81], v[92:93] op_sel_hi:[1,0,1] neg_lo:[0,0,1] neg_hi:[0,0,1]
	v_pk_fma_f32 v[94:95], v[74:75], v[80:81], v[94:95] op_sel_hi:[1,0,1] neg_lo:[0,0,1] neg_hi:[0,0,1]
	v_lshl_add_u64 v[96:97], v[140:141], 0, v[96:97]
	global_store_dwordx4 v[96:97], v[84:87], off
	s_nop 1
	v_cvt_pk_bf16_f32 v84, v88, v89
	v_cvt_pk_bf16_f32 v85, v90, v91
	v_cvt_pk_bf16_f32 v86, v92, v93
	v_cvt_pk_bf16_f32 v87, v94, v95
	global_store_dwordx4 v[96:97], v[84:87], off offset:32

; #define LAS __attribute__((address_space(3)))
; __device__ __forceinline__ float bflo(unsigned w) { return __uint_as_float(w << 16); }
; __device__ __forceinline__ float bfhi(unsigned w) { return __uint_as_float(w & 0xffff0000u); }
;     __device__ __forceinline__ void operator()(const f32x4 (&acc)[2][2][4][2], const Unit& u, int wr, int wc, int fr, int fq, const LAS float* rsl) const {
;         const int row0 = u.pm * 256 + wr * 64 + fr;
; #pragma unroll
;         for (int ai = 0; ai < 2; ++ai)
; #pragma unroll
;             for (int m = 0; m < 4; ++m) {
;                 const int row = row0 + ai * 128 + m * 16; const float rs = rsl[ai * 128 + wr * 64 + m * 16 + fr];
;                 if (u.pn < 14) {
; #pragma unroll
;                     for (int bj = 0; bj < 2; ++bj) {
;                         const f32x4 v0 = acc[ai][bj][m][0] * rs, v1 = acc[ai][bj][m][1] * rs;
;                         *(u32x4*)(P + (size_t)row * PW + u.pn * 256 + bj * 128 + wc * 32 + 8 * fq) = pack8(v0, v1);
;                     }
;                 } else if (wc == 0) {
;                     const f32x4 v0 = acc[ai][0][m][0] * rs, v1 = acc[ai][0][m][1] * rs;
;                     const u32x4 hi = pack8(v0, v1);
;                     const f32x4 d0 = (f32x4){v0[0] - bflo(hi.x), v0[1] - bfhi(hi.x), v0[2] - bflo(hi.y), v0[3] - bfhi(hi.y)};
;                     const f32x4 d1 = (f32x4){v1[0] - bflo(hi.z), v1[1] - bfhi(hi.z), v1[2] - bflo(hi.w), v1[3] - bfhi(hi.w)};
;                     bf16_t* lp = lr + (size_t)row * 64 + (fq >> 1) * 32 + (fq & 1) * 8;
;                     *(u32x4*)lp = hi; *(u32x4*)(lp + 16) = pack8(d0, d1);
;                 }
;             }
;     }
.LBB0_580:
	s_nop 1
	v_mov_b32_e32 v64, v188
	s_nop 0
	v_add_u32_e32 v66, 0x80, v158
	s_and_b64 vcc, exec, s[14:15]
	s_mov_b64 s[28:29], -1
	s_cbranch_vccnz .LBB0_584
	s_and_b64 vcc, exec, s[12:13]
	s_cbranch_vccnz .LBB0_583
	s_waitcnt lgkmcnt(0)
	v_pk_mul_f32 v[70:71], v[62:63], v[64:65] op_sel_hi:[1,0]
	v_pk_mul_f32 v[68:69], v[60:61], v[64:65] op_sel_hi:[1,0]
	v_pk_mul_f32 v[72:73], v[58:59], v[64:65] op_sel_hi:[1,0]
	v_pk_mul_f32 v[74:75], v[56:57], v[64:65] op_sel_hi:[1,0]
	v_cvt_pk_bf16_f32 v68, v68, v69
	v_cvt_pk_bf16_f32 v69, v70, v71
	v_cvt_pk_bf16_f32 v70, v74, v75
	v_cvt_pk_bf16_f32 v71, v72, v73
	v_ashrrev_i32_e32 v67, 31, v66
	v_lshlrev_b32_e32 v72, 16, v68
	v_and_b32_e32 v73, 0xffff0000, v68
	v_lshlrev_b32_e32 v74, 16, v69
	v_and_b32_e32 v75, 0xffff0000, v69
	v_lshlrev_b32_e32 v76, 16, v70
	v_and_b32_e32 v77, 0xffff0000, v70
	v_lshlrev_b32_e32 v78, 16, v71
	v_and_b32_e32 v79, 0xffff0000, v71
	v_lshlrev_b64 v[80:81], 7, v[66:67]
	v_pk_fma_f32 v[72:73], v[60:61], v[64:65], v[72:73] op_sel_hi:[1,0,1] neg_lo:[0,0,1] neg_hi:[0,0,1]
	v_pk_fma_f32 v[74:75], v[62:63], v[64:65], v[74:75] op_sel_hi:[1,0,1] neg_lo:[0,0,1] neg_hi:[0,0,1]
	v_pk_fma_f32 v[76:77], v[56:57], v[64:65], v[76:77] op_sel_hi:[1,0,1] neg_lo:[0,0,1] neg_hi:[0,0,1]
	v_pk_fma_f32 v[78:79], v[58:59], v[64:65], v[78:79] op_sel_hi:[1,0,1] neg_lo:[0,0,1] neg_hi:[0,0,1]
	v_lshl_add_u64 v[80:81], v[140:141], 0, v[80:81]
	global_store_dwordx4 v[80:81], v[68:71], off
	s_nop 1
	v_cvt_pk_bf16_f32 v68, v72, v73
	v_cvt_pk_bf16_f32 v69, v74, v75
	v_cvt_pk_bf16_f32 v70, v76, v77
	v_cvt_pk_bf16_f32 v71, v78, v79
	global_store_dwordx4 v[80:81], v[68:71], off offset:32

; #define LAS __attribute__((address_space(3)))
; __device__ __forceinline__ float bflo(unsigned w) { return __uint_as_float(w << 16); }
; __device__ __forceinline__ float bfhi(unsigned w) { return __uint_as_float(w & 0xffff0000u); }
;     __device__ __forceinline__ void operator()(const f32x4 (&acc)[2][2][4][2], const Unit& u, int wr, int wc, int fr, int fq, const LAS float* rsl) const {
;         const int row0 = u.pm * 256 + wr * 64 + fr;
; #pragma unroll
;         for (int ai = 0; ai < 2; ++ai)
; #pragma unroll
;             for (int m = 0; m < 4; ++m) {
;                 const int row = row0 + ai * 128 + m * 16; const float rs = rsl[ai * 128 + wr * 64 + m * 16 + fr];
;                 if (u.pn < 14) {
; #pragma unroll
;                     for (int bj = 0; bj < 2; ++bj) {
;                         const f32x4 v0 = acc[ai][bj][m][0] * rs, v1 = acc[ai][bj][m][1] * rs;
;                         *(u32x4*)(P + (size_t)row * PW + u.pn * 256 + bj * 128 + wc * 32 + 8 * fq) = pack8(v0, v1);
;                     }
;                 } else if (wc == 0) {
;                     const f32x4 v0 = acc[ai][0][m][0] * rs, v1 = acc[ai][0][m][1] * rs;
;                     const u32x4 hi = pack8(v0, v1);
;                     const f32x4 d0 = (f32x4){v0[0] - bflo(hi.x), v0[1] - bfhi(hi.x), v0[2] - bflo(hi.y), v0[3] - bfhi(hi.y)};
;                     const f32x4 d1 = (f32x4){v1[0] - bflo(hi.z), v1[1] - bfhi(hi.z), v1[2] - bflo(hi.w), v1[3] - bfhi(hi.w)};
;                     bf16_t* lp = lr + (size_t)row * 64 + (fq >> 1) * 32 + (fq & 1) * 8;
;                     *(u32x4*)lp = hi; *(u32x4*)(lp + 16) = pack8(d0, d1);
;                 }
;             }
;     }
.LBB0_586:
	s_nop 1
	v_mov_b32_e32 v48, v189
	s_nop 0
	v_add_u32_e32 v50, 0x90, v158
	s_and_b64 vcc, exec, s[14:15]
	s_mov_b64 s[28:29], -1
	s_cbranch_vccnz .LBB0_590
	s_and_b64 vcc, exec, s[12:13]
	s_cbranch_vccnz .LBB0_589
	s_waitcnt lgkmcnt(0)
	v_pk_mul_f32 v[54:55], v[46:47], v[48:49] op_sel_hi:[1,0]
	v_pk_mul_f32 v[52:53], v[44:45], v[48:49] op_sel_hi:[1,0]
	v_pk_mul_f32 v[56:57], v[42:43], v[48:49] op_sel_hi:[1,0]
	v_pk_mul_f32 v[58:59], v[40:41], v[48:49] op_sel_hi:[1,0]
	v_cvt_pk_bf16_f32 v52, v52, v53
	v_cvt_pk_bf16_f32 v53, v54, v55
	v_cvt_pk_bf16_f32 v54, v58, v59
	v_cvt_pk_bf16_f32 v55, v56, v57
	v_ashrrev_i32_e32 v51, 31, v50
	v_lshlrev_b32_e32 v56, 16, v52
	v_and_b32_e32 v57, 0xffff0000, v52
	v_lshlrev_b32_e32 v58, 16, v53
	v_and_b32_e32 v59, 0xffff0000, v53
	v_lshlrev_b32_e32 v60, 16, v54
	v_and_b32_e32 v61, 0xffff0000, v54
	v_lshlrev_b32_e32 v62, 16, v55
	v_and_b32_e32 v63, 0xffff0000, v55
	v_lshlrev_b64 v[64:65], 7, v[50:51]
	v_pk_fma_f32 v[56:57], v[44:45], v[48:49], v[56:57] op_sel_hi:[1,0,1] neg_lo:[0,0,1] neg_hi:[0,0,1]
	v_pk_fma_f32 v[58:59], v[46:47], v[48:49], v[58:59] op_sel_hi:[1,0,1] neg_lo:[0,0,1] neg_hi:[0,0,1]
	v_pk_fma_f32 v[60:61], v[40:41], v[48:49], v[60:61] op_sel_hi:[1,0,1] neg_lo:[0,0,1] neg_hi:[0,0,1]
	v_pk_fma_f32 v[62:63], v[42:43], v[48:49], v[62:63] op_sel_hi:[1,0,1] neg_lo:[0,0,1] neg_hi:[0,0,1]
	v_lshl_add_u64 v[64:65], v[140:141], 0, v[64:65]
	global_store_dwordx4 v[64:65], v[52:55], off
	s_nop 1
	v_cvt_pk_bf16_f32 v52, v56, v57
	v_cvt_pk_bf16_f32 v53, v58, v59
	v_cvt_pk_bf16_f32 v54, v60, v61
	v_cvt_pk_bf16_f32 v55, v62, v63
	global_store_dwordx4 v[64:65], v[52:55], off offset:32

; #define LAS __attribute__((address_space(3)))
; __device__ __forceinline__ float bflo(unsigned w) { return __uint_as_float(w << 16); }
; __device__ __forceinline__ float bfhi(unsigned w) { return __uint_as_float(w & 0xffff0000u); }
;     __device__ __forceinline__ void operator()(const f32x4 (&acc)[2][2][4][2], const Unit& u, int wr, int wc, int fr, int fq, const LAS float* rsl) const {
;         const int row0 = u.pm * 256 + wr * 64 + fr;
; #pragma unroll
;         for (int ai = 0; ai < 2; ++ai)
; #pragma unroll
;             for (int m = 0; m < 4; ++m) {
;                 const int row = row0 + ai * 128 + m * 16; const float rs = rsl[ai * 128 + wr * 64 + m * 16 + fr];
;                 if (u.pn < 14) {
; #pragma unroll
;                     for (int bj = 0; bj < 2; ++bj) {
;                         const f32x4 v0 = acc[ai][bj][m][0] * rs, v1 = acc[ai][bj][m][1] * rs;
;                         *(u32x4*)(P + (size_t)row * PW + u.pn * 256 + bj * 128 + wc * 32 + 8 * fq) = pack8(v0, v1);
;                     }
;                 } else if (wc == 0) {
;                     const f32x4 v0 = acc[ai][0][m][0] * rs, v1 = acc[ai][0][m][1] * rs;
;                     const u32x4 hi = pack8(v0, v1);
;                     const f32x4 d0 = (f32x4){v0[0] - bflo(hi.x), v0[1] - bfhi(hi.x), v0[2] - bflo(hi.y), v0[3] - bfhi(hi.y)};
;                     const f32x4 d1 = (f32x4){v1[0] - bflo(hi.z), v1[1] - bfhi(hi.z), v1[2] - bflo(hi.w), v1[3] - bfhi(hi.w)};
;                     bf16_t* lp = lr + (size_t)row * 64 + (fq >> 1) * 32 + (fq & 1) * 8;
;                     *(u32x4*)lp = hi; *(u32x4*)(lp + 16) = pack8(d0, d1);
;                 }
;             }
;     }
.LBB0_592:
	s_nop 1
	v_mov_b32_e32 v32, v190
	s_nop 0
	v_add_u32_e32 v34, 0xa0, v158
	s_and_b64 vcc, exec, s[14:15]
	s_mov_b64 s[28:29], -1
	s_cbranch_vccnz .LBB0_596
	s_and_b64 vcc, exec, s[12:13]
	s_cbranch_vccnz .LBB0_595
	s_waitcnt lgkmcnt(0)
	v_pk_mul_f32 v[38:39], v[30:31], v[32:33] op_sel_hi:[1,0]
	v_pk_mul_f32 v[36:37], v[28:29], v[32:33] op_sel_hi:[1,0]
	v_pk_mul_f32 v[40:41], v[26:27], v[32:33] op_sel_hi:[1,0]
	v_pk_mul_f32 v[42:43], v[24:25], v[32:33] op_sel_hi:[1,0]
	v_cvt_pk_bf16_f32 v36, v36, v37
	v_cvt_pk_bf16_f32 v37, v38, v39
	v_cvt_pk_bf16_f32 v38, v42, v43
	v_cvt_pk_bf16_f32 v39, v40, v41
	v_ashrrev_i32_e32 v35, 31, v34
	v_lshlrev_b32_e32 v40, 16, v36
	v_and_b32_e32 v41, 0xffff0000, v36
	v_lshlrev_b32_e32 v42, 16, v37
	v_and_b32_e32 v43, 0xffff0000, v37
	v_lshlrev_b32_e32 v44, 16, v38
	v_and_b32_e32 v45, 0xffff0000, v38
	v_lshlrev_b32_e32 v46, 16, v39
	v_and_b32_e32 v47, 0xffff0000, v39
	v_lshlrev_b64 v[48:49], 7, v[34:35]
	v_pk_fma_f32 v[40:41], v[28:29], v[32:33], v[40:41] op_sel_hi:[1,0,1] neg_lo:[0,0,1] neg_hi:[0,0,1]
	v_pk_fma_f32 v[42:43], v[30:31], v[32:33], v[42:43] op_sel_hi:[1,0,1] neg_lo:[0,0,1] neg_hi:[0,0,1]
	v_pk_fma_f32 v[44:45], v[24:25], v[32:33], v[44:45] op_sel_hi:[1,0,1] neg_lo:[0,0,1] neg_hi:[0,0,1]
	v_pk_fma_f32 v[46:47], v[26:27], v[32:33], v[46:47] op_sel_hi:[1,0,1] neg_lo:[0,0,1] neg_hi:[0,0,1]
	v_lshl_add_u64 v[48:49], v[140:141], 0, v[48:49]
	global_store_dwordx4 v[48:49], v[36:39], off
	s_nop 1
	v_cvt_pk_bf16_f32 v36, v40, v41
	v_cvt_pk_bf16_f32 v37, v42, v43
	v_cvt_pk_bf16_f32 v38, v44, v45
	v_cvt_pk_bf16_f32 v39, v46, v47
	global_store_dwordx4 v[48:49], v[36:39], off offset:32

; #define LAS __attribute__((address_space(3)))
; __device__ __forceinline__ float bflo(unsigned w) { return __uint_as_float(w << 16); }
; __device__ __forceinline__ float bfhi(unsigned w) { return __uint_as_float(w & 0xffff0000u); }
;     __device__ __forceinline__ void operator()(const f32x4 (&acc)[2][2][4][2], const Unit& u, int wr, int wc, int fr, int fq, const LAS float* rsl) const {
;         const int row0 = u.pm * 256 + wr * 64 + fr;
; #pragma unroll
;         for (int ai = 0; ai < 2; ++ai)
; #pragma unroll
;             for (int m = 0; m < 4; ++m) {
;                 const int row = row0 + ai * 128 + m * 16; const float rs = rsl[ai * 128 + wr * 64 + m * 16 + fr];
;                 if (u.pn < 14) {
; #pragma unroll
;                     for (int bj = 0; bj < 2; ++bj) {
;                         const f32x4 v0 = acc[ai][bj][m][0] * rs, v1 = acc[ai][bj][m][1] * rs;
;                         *(u32x4*)(P + (size_t)row * PW + u.pn * 256 + bj * 128 + wc * 32 + 8 * fq) = pack8(v0, v1);
;                     }
;                 } else if (wc == 0) {
;                     const f32x4 v0 = acc[ai][0][m][0] * rs, v1 = acc[ai][0][m][1] * rs;
;                     const u32x4 hi = pack8(v0, v1);
;                     const f32x4 d0 = (f32x4){v0[0] - bflo(hi.x), v0[1] - bfhi(hi.x), v0[2] - bflo(hi.y), v0[3] - bfhi(hi.y)};
;                     const f32x4 d1 = (f32x4){v1[0] - bflo(hi.z), v1[1] - bfhi(hi.z), v1[2] - bflo(hi.w), v1[3] - bfhi(hi.w)};
;                     bf16_t* lp = lr + (size_t)row * 64 + (fq >> 1) * 32 + (fq & 1) * 8;
;                     *(u32x4*)lp = hi; *(u32x4*)(lp + 16) = pack8(d0, d1);
;                 }
;             }
;     }
.LBB0_598:
	s_nop 1
	v_mov_b32_e32 v16, v191
	s_nop 0
	v_add_u32_e32 v18, 0xb0, v158
	s_and_b64 vcc, exec, s[14:15]
	s_mov_b64 s[14:15], -1
	s_cbranch_vccz .LBB0_601
	s_andn2_b64 vcc, exec, s[14:15]
	s_cbranch_vccz .LBB0_604
